# new pipelined k-loop also in GLU and out-proj GEMMs; GLU epilogue loads hoisted; out-proj epilogue LDS-transposed dwordx4 stores
# speedup vs baseline: 1.0379x; 1.0169x over previous
.LBB0_142:
	s_mul_hi_i32 s0, s54, 0x2aaaaaab
	s_lshr_b32 s1, s0, 31
	s_ashr_i32 s6, s0, 2
	s_add_i32 s6, s6, s1
	s_mul_i32 s0, s6, 24
	v_readlane_b32 s4, v230, 1
	s_sub_i32 s8, s54, s0
	s_lshl_b32 s0, s6, 20
	v_readlane_b32 s5, v230, 2
	s_add_i32 s1, s4, s0
	v_readlane_b32 s4, v229, 47
	v_mov_b32_e32 v2, v194
	v_readlane_b32 s60, v230, 18
	s_lshl_b32 s2, s8, 20
	s_mul_i32 s4, s4, 0x1800000
	v_readlane_b32 s70, v230, 28
	v_ashrrev_i32_e32 v3, 6, v2
	v_bfe_u32 v4, v2, 3, 3
	v_readlane_b32 s5, v229, 48
	s_add_i32 s4, s2, s4
	v_and_b32_e32 v204, 3, v3
	v_lshlrev_b32_e32 v7, 2, v3
	v_lshlrev_b32_e32 v208, 12, v3
	v_lshlrev_b32_e32 v8, 4, v2
	v_and_b32_e32 v9, 48, v2
	s_movk_i32 s2, 0x70
	v_lshlrev_b32_e32 v3, 17, v3
	v_lshlrev_b32_e32 v11, 12, v4
	s_sub_i32 s1, s1, s70
	v_and_b32_e32 v10, 0x70, v8
	v_bitop3_b32 v8, v8, v9, s2 bitop3:0x6c
	v_or_b32_e32 v12, v11, v3
	v_readfirstlane_b32 s5, v208
	v_add3_u32 v13, v8, s1, v12
	s_mov_b32 m0, s5
	v_add_u32_e32 v12, s4, v12
	buffer_load_dwordx4 v13, s[44:47], 0 offen lds
	v_or_b32_e32 v13, 1, v7
	v_lshl_or_b32 v14, v13, 3, v4
	v_lshrrev_b32_e32 v15, 1, v14
	v_xor_b32_e32 v15, v15, v2
	v_lshlrev_b32_e32 v209, 10, v13
	v_lshlrev_b32_e32 v13, 4, v15
	v_and_b32_e32 v13, 0x70, v13
	v_lshlrev_b32_e32 v14, 12, v14
	v_readfirstlane_b32 s5, v209
	v_add3_u32 v15, v14, s1, v13
	s_mov_b32 m0, s5
	v_bitop3_b32 v9, v12, v10, v9 bitop3:0xf6
	buffer_load_dwordx4 v15, s[44:47], 0 offen lds
	v_or_b32_e32 v15, 2, v7
	v_lshl_or_b32 v16, v15, 3, v4
	v_lshrrev_b32_e32 v17, 1, v16
	v_xor_b32_e32 v17, v17, v2
	v_lshlrev_b32_e32 v210, 10, v15
	v_lshlrev_b32_e32 v15, 4, v17
	v_and_b32_e32 v15, 0x70, v15
	v_lshlrev_b32_e32 v16, 12, v16
	v_readfirstlane_b32 s5, v210
	v_or_b32_e32 v7, 3, v7
	v_add3_u32 v17, v16, s1, v15
	s_mov_b32 m0, s5
	v_lshl_or_b32 v4, v7, 3, v4
	buffer_load_dwordx4 v17, s[44:47], 0 offen lds
	v_lshrrev_b32_e32 v17, 1, v4
	v_xor_b32_e32 v17, v17, v2
	v_lshlrev_b32_e32 v211, 10, v7
	v_lshlrev_b32_e32 v7, 4, v17
	v_and_b32_e32 v7, 0x70, v7
	v_lshlrev_b32_e32 v4, 12, v4
	v_add3_u32 v17, v4, s1, v7
	v_readfirstlane_b32 s1, v211
	s_mov_b32 m0, s1
	v_add_u32_e32 v10, s4, v14
	buffer_load_dwordx4 v17, s[44:47], 0 offen lds
	v_add_u32_e32 v17, 0x8000, v208
	v_or_b32_e32 v10, v13, v10
	v_readfirstlane_b32 s1, v17
	s_mov_b32 m0, s1
	v_add_u32_e32 v4, s4, v4
	buffer_load_dwordx4 v9, s[44:47], 0 offen lds
	v_add_u32_e32 v9, 0x8000, v209
	v_or_b32_e32 v4, v7, v4
	v_readfirstlane_b32 s1, v9
	s_mov_b32 m0, s1
	v_add_u32_e32 v9, 0x8000, v210
	buffer_load_dwordx4 v10, s[44:47], 0 offen lds
	v_add_u32_e32 v10, s4, v16
	v_readfirstlane_b32 s1, v9
	v_add_u32_e32 v9, 0x8000, v211
	v_or_b32_e32 v10, v15, v10
	s_mov_b32 m0, s1
	v_readfirstlane_b32 s1, v9
	buffer_load_dwordx4 v10, s[44:47], 0 offen lds
	s_mov_b32 m0, s1
	s_lshl_b32 s1, s54, 20
	buffer_load_dwordx4 v4, s[44:47], 0 offen lds
	s_add_i32 s4, s57, s1
	v_bfe_u32 v205, v2, 4, 2
	v_and_b32_e32 v1, 15, v2
	v_lshrrev_b32_e32 v5, 1, v2
	v_bfe_u32 v6, v2, 1, 3
	v_ashrrev_i32_e32 v212, 8, v2
	v_add_u32_e32 v2, s4, v3
	v_readlane_b32 s5, v229, 15
	v_add3_u32 v2, v2, v11, v7
	s_mul_i32 s4, s6, 0x1800000
	s_add_i32 s5, s5, s1
	v_subrev_u32_e32 v216, s4, v2
	v_add_u32_e32 v2, s5, v3
	v_readlane_b32 s5, v229, 17
	v_add3_u32 v2, v2, v11, v15
	s_add_i32 s5, s5, s1
	v_subrev_u32_e32 v217, s4, v2
	v_add_u32_e32 v2, s5, v3
	v_readlane_b32 s5, v229, 46
	v_add3_u32 v2, v2, v11, v13
	s_add_i32 s1, s1, s5
	v_subrev_u32_e32 v218, s4, v2
	v_add_u32_e32 v2, s1, v8
	v_readlane_b32 s1, v229, 14
	v_add3_u32 v2, v2, v3, v11
	s_add_i32 s1, s1, s0
	v_subrev_u32_e32 v219, s4, v2
	v_add_u32_e32 v2, s1, v3
	v_readlane_b32 s1, v229, 16
	s_add_i32 s1, s1, s0
	v_add3_u32 v220, v2, v11, v7
	v_add_u32_e32 v2, s1, v3
	v_readlane_b32 s1, v229, 18
	s_add_i32 s1, s1, s0
	v_add3_u32 v221, v2, v11, v15
	v_add_u32_e32 v2, s1, v3
	v_readlane_b32 s1, v229, 19
	s_add_i32 s0, s0, s1
	v_bitop3_b32 v5, v205, v5, 7 bitop3:0x78
	v_bitop3_b32 v6, v205, v6, 4 bitop3:0x36
	v_add3_u32 v222, v2, v11, v13
	v_add_u32_e32 v2, s0, v8
	v_mov_b32_e32 v34, 0
	v_lshlrev_b32_e32 v206, 7, v1
	v_lshlrev_b32_e32 v207, 13, v204
	s_mov_b32 s2, 0
	v_lshlrev_b32_e32 v213, 14, v212
	v_lshlrev_b32_e32 v214, 4, v5
	v_lshlrev_b32_e32 v215, 4, v6
	v_add3_u32 v223, v2, v3, v11
	s_mov_b32 s7, 0
	v_mov_b32_e32 v35, v34
	v_mov_b32_e32 v36, v34
	v_mov_b32_e32 v37, v34
	v_mov_b32_e32 v38, v34
	v_mov_b32_e32 v39, v34
	v_mov_b32_e32 v40, v34
	v_mov_b32_e32 v41, v34
	v_mov_b32_e32 v42, v34
	v_mov_b32_e32 v43, v34
	v_mov_b32_e32 v44, v34
	v_mov_b32_e32 v45, v34
	v_mov_b32_e32 v46, v34
	v_mov_b32_e32 v47, v34
	v_mov_b32_e32 v48, v34
	v_mov_b32_e32 v49, v34
	v_mov_b32_e32 v50, v34
	v_mov_b32_e32 v51, v34
	v_mov_b32_e32 v52, v34
	v_mov_b32_e32 v53, v34
	v_mov_b32_e32 v54, v34
	v_mov_b32_e32 v55, v34
	v_mov_b32_e32 v56, v34
	v_mov_b32_e32 v57, v34
	v_mov_b32_e32 v58, v34
	v_mov_b32_e32 v59, v34
	v_mov_b32_e32 v60, v34
	v_mov_b32_e32 v61, v34
	v_mov_b32_e32 v62, v34
	v_mov_b32_e32 v63, v34
	v_mov_b32_e32 v64, v34
	v_mov_b32_e32 v65, v34
	v_mov_b32_e32 v66, v34
	v_mov_b32_e32 v67, v34
	v_mov_b32_e32 v68, v34
	v_mov_b32_e32 v69, v34
	v_mov_b32_e32 v70, v34
	v_mov_b32_e32 v71, v34
	v_mov_b32_e32 v72, v34
	v_mov_b32_e32 v73, v34
	v_mov_b32_e32 v74, v34
	v_mov_b32_e32 v75, v34
	v_mov_b32_e32 v76, v34
	v_mov_b32_e32 v77, v34
	v_mov_b32_e32 v78, v34
	v_mov_b32_e32 v79, v34
	v_mov_b32_e32 v80, v34
	v_mov_b32_e32 v81, v34
	v_mov_b32_e32 v82, v34
	v_mov_b32_e32 v83, v34
	v_mov_b32_e32 v84, v34
	v_mov_b32_e32 v85, v34
	v_mov_b32_e32 v86, v34
	v_mov_b32_e32 v87, v34
	v_mov_b32_e32 v88, v34
	v_mov_b32_e32 v89, v34
	v_mov_b32_e32 v90, v34
	v_mov_b32_e32 v91, v34
	v_mov_b32_e32 v92, v34
	v_mov_b32_e32 v93, v34
	v_mov_b32_e32 v94, v34
	v_mov_b32_e32 v95, v34
	v_mov_b32_e32 v96, v34
	v_mov_b32_e32 v97, v34
	v_mov_b32_e32 v98, v34
	v_mov_b32_e32 v99, v34
	v_mov_b32_e32 v100, v34
	v_mov_b32_e32 v101, v34
	v_mov_b32_e32 v102, v34
	v_mov_b32_e32 v103, v34
	v_mov_b32_e32 v104, v34
	v_mov_b32_e32 v105, v34
	v_mov_b32_e32 v106, v34
	v_mov_b32_e32 v107, v34
	v_mov_b32_e32 v108, v34
	v_mov_b32_e32 v109, v34
	v_mov_b32_e32 v110, v34
	v_mov_b32_e32 v111, v34
	v_mov_b32_e32 v112, v34
	v_mov_b32_e32 v113, v34
	v_mov_b32_e32 v114, v34
	v_mov_b32_e32 v115, v34
	v_mov_b32_e32 v116, v34
	v_mov_b32_e32 v117, v34
	v_mov_b32_e32 v118, v34
	v_mov_b32_e32 v119, v34
	v_mov_b32_e32 v120, v34
	v_mov_b32_e32 v121, v34
	v_mov_b32_e32 v122, v34
	v_mov_b32_e32 v123, v34
	v_mov_b32_e32 v124, v34
	v_mov_b32_e32 v125, v34
	v_mov_b32_e32 v126, v34
	v_mov_b32_e32 v127, v34
	v_mov_b32_e32 v128, v34
	v_mov_b32_e32 v129, v34
	v_mov_b32_e32 v30, v34
	v_mov_b32_e32 v31, v34
	v_mov_b32_e32 v32, v34
	v_mov_b32_e32 v33, v34
	v_mov_b32_e32 v26, v34
	v_mov_b32_e32 v27, v34
	v_mov_b32_e32 v28, v34
	v_mov_b32_e32 v29, v34
	v_mov_b32_e32 v22, v34
	v_mov_b32_e32 v23, v34
	v_mov_b32_e32 v24, v34
	v_mov_b32_e32 v25, v34
	v_mov_b32_e32 v18, v34
	v_mov_b32_e32 v19, v34
	v_mov_b32_e32 v20, v34
	v_mov_b32_e32 v21, v34
	v_mov_b32_e32 v14, v34
	v_mov_b32_e32 v15, v34
	v_mov_b32_e32 v16, v34
	v_mov_b32_e32 v17, v34
	v_mov_b32_e32 v10, v34
	v_mov_b32_e32 v11, v34
	v_mov_b32_e32 v12, v34
	v_mov_b32_e32 v13, v34
	v_mov_b32_e32 v6, v34
	v_mov_b32_e32 v7, v34
	v_mov_b32_e32 v8, v34
	v_mov_b32_e32 v9, v34
	v_mov_b32_e32 v2, v34
	v_mov_b32_e32 v3, v34
	v_mov_b32_e32 v4, v34
	v_mov_b32_e32 v5, v34
	v_readlane_b32 s61, v230, 19
	v_readlane_b32 s62, v230, 20
	v_readlane_b32 s63, v230, 21
	v_readlane_b32 s64, v230, 22
	v_readlane_b32 s65, v230, 23
	v_readlane_b32 s66, v230, 24
	v_readlane_b32 s67, v230, 25
	v_readlane_b32 s68, v230, 26
	v_readlane_b32 s69, v230, 27
	v_readlane_b32 s71, v230, 29
	v_readlane_b32 s72, v230, 30
	v_readlane_b32 s73, v230, 31
	v_readlane_b32 s74, v230, 32
	v_readlane_b32 s75, v230, 33
	v_readfirstlane_b32 s12, v208
	v_readfirstlane_b32 s16, v212
	v_add3_u32 v250, v213, v206, v214
	v_add3_u32 v251, v213, v206, v215
	v_add3_u32 v252, v207, v206, v214
	v_add3_u32 v253, v207, v206, v215
	s_mov_b32 s10, 0
	s_mov_b32 s11, 0
	s_waitcnt vmcnt(0)
	s_barrier
	s_add_i32 s14, s12, 0x10000
	s_mov_b32 m0, s14
	s_nop 0
	buffer_load_dwordx4 v223, s[44:47], s11 offen lds
	s_add_u32 m0, s14, 0x400
	s_nop 0
	buffer_load_dwordx4 v222, s[44:47], s11 offen lds
	s_add_u32 m0, s14, 0x800
	s_nop 0
	buffer_load_dwordx4 v221, s[44:47], s11 offen lds
	s_add_u32 m0, s14, 0xc00
	s_nop 0
	buffer_load_dwordx4 v220, s[44:47], s11 offen lds
	s_add_u32 m0, s14, 0x8000
	s_nop 0
	buffer_load_dwordx4 v219, s[44:47], s11 offen lds
	s_add_u32 m0, s14, 0x8400
	s_nop 0
	buffer_load_dwordx4 v218, s[44:47], s11 offen lds
	s_add_u32 m0, s14, 0x8800
	s_nop 0
	buffer_load_dwordx4 v217, s[44:47], s11 offen lds
	s_add_u32 m0, s14, 0x8c00
	s_nop 0
	buffer_load_dwordx4 v216, s[44:47], s11 offen lds
	s_movk_i32 s11, 0x80
	ds_read_b128 v[162:165], v252 offset:32768
	ds_read_b128 v[166:169], v252 offset:34816
	ds_read_b128 v[170:173], v252 offset:36864
	ds_read_b128 v[174:177], v252 offset:38912
	ds_read_b128 v[146:149], v250 offset:8192
	ds_read_b128 v[150:153], v250 offset:10240
	ds_read_b128 v[154:157], v250 offset:12288
	ds_read_b128 v[158:161], v250 offset:14336
	ds_read_b128 v[130:133], v250
	ds_read_b128 v[134:137], v250 offset:2048
	ds_read_b128 v[138:141], v250 offset:4096
	ds_read_b128 v[142:145], v250 offset:6144
	s_movk_i32 s15, 30

.LBB0_798:
	s_lshl_b32 s0, s29, 19
	s_and_b32 s4, s0, 0x200000
	s_bfe_u32 s0, s29, 0x20003
	s_ashr_i32 s37, s30, 3
	s_lshl_b32 s8, s30, 2
	s_lshl_b32 s11, s0, 22
	s_lshl_b32 s36, s0, 3
	s_and_b32 s50, s37, 0xffffffe0
	s_and_b32 s0, s8, 24
	s_bfe_u32 s31, s30, 0x30003
	s_or_b32 s0, s50, s0
	v_readlane_b32 s60, v230, 18
	s_or_b32 s0, s0, s31
	v_readlane_b32 s61, v230, 19
	v_readlane_b32 s62, v230, 20
	v_readlane_b32 s68, v230, 26
	v_readlane_b32 s69, v230, 27
	s_bfe_u32 s1, s30, 0x20006
	s_and_b32 s8, s8, 4
	s_lshl_b32 s10, s0, 19
	v_readlane_b32 s70, v230, 28
	s_mov_b64 s[60:61], s[68:69]
	s_or_b32 s8, s8, s1
	s_add_i32 s10, s96, s10
	s_mov_b32 s62, s70
	s_sub_i32 s51, s10, s62
	s_lshl_b32 s10, s8, 19
	s_add_i32 s10, s2, s10
	v_mov_b32_e32 v2, v194
	s_sub_i32 s54, s10, s62
	s_movk_i32 s10, 0x70
	v_ashrrev_i32_e32 v3, 6, v2
	v_bfe_u32 v4, v2, 3, 3
	v_lshlrev_b32_e32 v8, 4, v2
	v_and_b32_e32 v9, 48, v2
	v_and_b32_e32 v1, 3, v3
	v_lshlrev_b32_e32 v7, 2, v3
	v_lshlrev_b32_e32 v208, 12, v3
	v_bitop3_b32 v8, v8, v9, s10 bitop3:0x6c
	v_lshlrev_b32_e32 v3, 16, v3
	v_lshlrev_b32_e32 v9, 11, v4
	v_or_b32_e32 v10, v9, v3
	v_readfirstlane_b32 s55, v208
	v_add3_u32 v11, v8, s51, v10
	s_mov_b32 m0, s55
	v_add3_u32 v10, v8, s54, v10
	buffer_load_dwordx4 v11, s[44:47], 0 offen lds
	v_or_b32_e32 v11, 1, v7
	v_lshl_or_b32 v12, v11, 3, v4
	v_lshrrev_b32_e32 v13, 1, v12
	v_xor_b32_e32 v13, v13, v2
	v_lshlrev_b32_e32 v209, 10, v11
	v_lshlrev_b32_e32 v11, 4, v13
	v_and_b32_e32 v11, 0x70, v11
	v_lshl_or_b32 v12, v12, 11, v11
	v_readfirstlane_b32 s55, v209
	v_add_u32_e32 v13, s51, v12
	s_mov_b32 m0, s55
	v_add_u32_e32 v12, s54, v12
	buffer_load_dwordx4 v13, s[44:47], 0 offen lds
	v_or_b32_e32 v13, 2, v7
	v_lshl_or_b32 v14, v13, 3, v4
	v_lshrrev_b32_e32 v15, 1, v14
	v_xor_b32_e32 v15, v15, v2
	v_lshlrev_b32_e32 v210, 10, v13
	v_lshlrev_b32_e32 v13, 4, v15
	v_and_b32_e32 v13, 0x70, v13
	v_lshl_or_b32 v14, v14, 11, v13
	v_readfirstlane_b32 s55, v210
	v_or_b32_e32 v7, 3, v7
	v_add_u32_e32 v15, s51, v14
	s_mov_b32 m0, s55
	v_lshl_or_b32 v4, v7, 3, v4
	buffer_load_dwordx4 v15, s[44:47], 0 offen lds
	v_lshrrev_b32_e32 v15, 1, v4
	v_xor_b32_e32 v15, v15, v2
	v_lshlrev_b32_e32 v211, 10, v7
	v_lshlrev_b32_e32 v7, 4, v15
	v_and_b32_e32 v7, 0x70, v7
	v_lshl_or_b32 v4, v4, 11, v7
	v_add_u32_e32 v15, s51, v4
	v_readfirstlane_b32 s51, v211
	s_mov_b32 m0, s51
	v_add_u32_e32 v4, s54, v4
	buffer_load_dwordx4 v15, s[44:47], 0 offen lds
	v_add_u32_e32 v15, 0x8000, v208
	s_lshl_b32 s5, s1, 19
	v_readfirstlane_b32 s51, v15
	s_mov_b32 m0, s51
	v_bfe_u32 v204, v2, 4, 2
	buffer_load_dwordx4 v10, s[44:47], 0 offen lds
	v_add_u32_e32 v10, 0x8000, v209
	v_and_b32_e32 v205, 15, v2
	v_readfirstlane_b32 s51, v10
	v_add_u32_e32 v10, 0x8000, v210
	s_mov_b32 m0, s51
	v_readfirstlane_b32 s51, v10
	v_add_u32_e32 v10, 0x8000, v211
	buffer_load_dwordx4 v12, s[44:47], 0 offen lds
	v_add_u32_e32 v12, s54, v14
	s_mov_b32 m0, s51
	v_readfirstlane_b32 s51, v10
	buffer_load_dwordx4 v12, s[44:47], 0 offen lds
	s_mov_b32 m0, s51
	s_add_i32 s51, s9, s4
	buffer_load_dwordx4 v4, s[44:47], 0 offen lds
	s_add_i32 s51, s51, s5
	v_lshrrev_b32_e32 v5, 1, v2
	v_bfe_u32 v6, v2, 1, 3
	v_ashrrev_i32_e32 v212, 8, v2
	v_add_u32_e32 v2, s51, v3
	s_add_i32 s51, s13, s4
	s_add_i32 s51, s51, s5
	v_add3_u32 v216, v2, v9, v7
	v_add_u32_e32 v2, s51, v3
	s_add_i32 s51, s27, s4
	s_add_i32 s51, s51, s5
	s_or_b32 s4, s5, s4
	v_add3_u32 v217, v2, v9, v13
	v_add_u32_e32 v2, s51, v3
	s_add_i32 s4, s4, s28
	v_add3_u32 v218, v2, v9, v11
	v_add_u32_e32 v2, s4, v8
	s_lshl_b32 s4, s37, 19
	s_and_b32 s4, s4, 0xff000000
	v_readlane_b32 s5, v229, 27
	s_add_i32 s5, s5, s4
	s_lshl_b32 s35, s31, 19
	s_add_i32 s5, s5, s11
	s_add_i32 s5, s5, s35
	v_add3_u32 v219, v2, v3, v9
	v_add_u32_e32 v2, s5, v3
	v_readlane_b32 s5, v229, 28
	s_add_i32 s5, s5, s4
	s_add_i32 s5, s5, s11
	s_add_i32 s5, s5, s35
	v_add3_u32 v220, v2, v9, v7
	v_add_u32_e32 v2, s5, v3
	v_readlane_b32 s5, v229, 29
	s_add_i32 s4, s5, s4
	s_add_i32 s4, s4, s11
	s_add_i32 s4, s4, s35
	v_add3_u32 v221, v2, v9, v13
	v_add_u32_e32 v2, s4, v3
	s_or_b32 s4, s50, s36
	s_or_b32 s4, s4, s31
	s_lshl_b32 s4, s4, 19
	v_readlane_b32 s5, v229, 30
	s_add_i32 s4, s4, s5
	v_bitop3_b32 v5, v204, v5, 7 bitop3:0x78
	v_bitop3_b32 v6, v204, v6, 4 bitop3:0x36
	v_add3_u32 v222, v2, v9, v11
	v_add_u32_e32 v2, s4, v8
	v_mov_b32_e32 v38, 0
	s_ashr_i32 s1, s0, 31
	v_lshlrev_b32_e32 v206, 7, v205
	v_lshlrev_b32_e32 v207, 13, v1
	s_mov_b32 s10, 0
	v_lshlrev_b32_e32 v213, 14, v212
	v_lshlrev_b32_e32 v214, 4, v5
	v_lshlrev_b32_e32 v215, 4, v6
	v_add3_u32 v223, v2, v3, v9
	s_mov_b32 s11, 0
	v_mov_b32_e32 v39, v38
	v_mov_b32_e32 v40, v38
	v_mov_b32_e32 v41, v38
	v_mov_b32_e32 v46, v38
	v_mov_b32_e32 v47, v38
	v_mov_b32_e32 v48, v38
	v_mov_b32_e32 v49, v38
	v_mov_b32_e32 v30, v38
	v_mov_b32_e32 v31, v38
	v_mov_b32_e32 v32, v38
	v_mov_b32_e32 v33, v38
	v_mov_b32_e32 v42, v38
	v_mov_b32_e32 v43, v38
	v_mov_b32_e32 v44, v38
	v_mov_b32_e32 v45, v38
	v_mov_b32_e32 v54, v38
	v_mov_b32_e32 v55, v38
	v_mov_b32_e32 v56, v38
	v_mov_b32_e32 v57, v38
	v_mov_b32_e32 v62, v38
	v_mov_b32_e32 v63, v38
	v_mov_b32_e32 v64, v38
	v_mov_b32_e32 v65, v38
	v_mov_b32_e32 v50, v38
	v_mov_b32_e32 v51, v38
	v_mov_b32_e32 v52, v38
	v_mov_b32_e32 v53, v38
	v_mov_b32_e32 v58, v38
	v_mov_b32_e32 v59, v38
	v_mov_b32_e32 v60, v38
	v_mov_b32_e32 v61, v38
	v_mov_b32_e32 v70, v38
	v_mov_b32_e32 v71, v38
	v_mov_b32_e32 v72, v38
	v_mov_b32_e32 v73, v38
	v_mov_b32_e32 v78, v38
	v_mov_b32_e32 v79, v38
	v_mov_b32_e32 v80, v38
	v_mov_b32_e32 v81, v38
	v_mov_b32_e32 v66, v38
	v_mov_b32_e32 v67, v38
	v_mov_b32_e32 v68, v38
	v_mov_b32_e32 v69, v38
	v_mov_b32_e32 v74, v38
	v_mov_b32_e32 v75, v38
	v_mov_b32_e32 v76, v38
	v_mov_b32_e32 v77, v38
	v_mov_b32_e32 v86, v38
	v_mov_b32_e32 v87, v38
	v_mov_b32_e32 v88, v38
	v_mov_b32_e32 v89, v38
	v_mov_b32_e32 v94, v38
	v_mov_b32_e32 v95, v38
	v_mov_b32_e32 v96, v38
	v_mov_b32_e32 v97, v38
	v_mov_b32_e32 v82, v38
	v_mov_b32_e32 v83, v38
	v_mov_b32_e32 v84, v38
	v_mov_b32_e32 v85, v38
	v_mov_b32_e32 v90, v38
	v_mov_b32_e32 v91, v38
	v_mov_b32_e32 v92, v38
	v_mov_b32_e32 v93, v38
	v_mov_b32_e32 v102, v38
	v_mov_b32_e32 v103, v38
	v_mov_b32_e32 v104, v38
	v_mov_b32_e32 v105, v38
	v_mov_b32_e32 v110, v38
	v_mov_b32_e32 v111, v38
	v_mov_b32_e32 v112, v38
	v_mov_b32_e32 v113, v38
	v_mov_b32_e32 v98, v38
	v_mov_b32_e32 v99, v38
	v_mov_b32_e32 v100, v38
	v_mov_b32_e32 v101, v38
	v_mov_b32_e32 v106, v38
	v_mov_b32_e32 v107, v38
	v_mov_b32_e32 v108, v38
	v_mov_b32_e32 v109, v38
	v_mov_b32_e32 v118, v38
	v_mov_b32_e32 v119, v38
	v_mov_b32_e32 v120, v38
	v_mov_b32_e32 v121, v38
	v_mov_b32_e32 v126, v38
	v_mov_b32_e32 v127, v38
	v_mov_b32_e32 v128, v38
	v_mov_b32_e32 v129, v38
	v_mov_b32_e32 v114, v38
	v_mov_b32_e32 v115, v38
	v_mov_b32_e32 v116, v38
	v_mov_b32_e32 v117, v38
	v_mov_b32_e32 v122, v38
	v_mov_b32_e32 v123, v38
	v_mov_b32_e32 v124, v38
	v_mov_b32_e32 v125, v38
	v_mov_b32_e32 v26, v38
	v_mov_b32_e32 v27, v38
	v_mov_b32_e32 v28, v38
	v_mov_b32_e32 v29, v38
	v_mov_b32_e32 v14, v38
	v_mov_b32_e32 v15, v38
	v_mov_b32_e32 v16, v38
	v_mov_b32_e32 v17, v38
	v_mov_b32_e32 v34, v38
	v_mov_b32_e32 v35, v38
	v_mov_b32_e32 v36, v38
	v_mov_b32_e32 v37, v38
	v_mov_b32_e32 v22, v38
	v_mov_b32_e32 v23, v38
	v_mov_b32_e32 v24, v38
	v_mov_b32_e32 v25, v38
	v_mov_b32_e32 v6, v38
	v_mov_b32_e32 v7, v38
	v_mov_b32_e32 v8, v38
	v_mov_b32_e32 v9, v38
	v_mov_b32_e32 v2, v38
	v_mov_b32_e32 v3, v38
	v_mov_b32_e32 v4, v38
	v_mov_b32_e32 v5, v38
	v_mov_b32_e32 v10, v38
	v_mov_b32_e32 v11, v38
	v_mov_b32_e32 v12, v38
	v_mov_b32_e32 v13, v38
	v_mov_b32_e32 v18, v38
	v_mov_b32_e32 v19, v38
	v_mov_b32_e32 v20, v38
	v_mov_b32_e32 v21, v38
	v_readlane_b32 s63, v230, 21
	v_readlane_b32 s64, v230, 22
	v_readlane_b32 s65, v230, 23
	v_readlane_b32 s66, v230, 24
	v_readlane_b32 s67, v230, 25
	v_readlane_b32 s71, v230, 29
	v_readlane_b32 s72, v230, 30
	v_readlane_b32 s73, v230, 31
	v_readlane_b32 s74, v230, 32
	v_readlane_b32 s75, v230, 33
	v_readfirstlane_b32 s16, v208
	v_add3_u32 v250, v213, v206, v214
	v_add3_u32 v251, v213, v206, v215
	v_add3_u32 v252, v207, v206, v214
	v_add3_u32 v253, v207, v206, v215
	s_mov_b32 s14, 0
	s_mov_b32 s15, 0
	s_waitcnt vmcnt(0)
	s_barrier
	s_add_i32 s18, s16, 0x10000
	s_mov_b32 m0, s18
	s_nop 0
	buffer_load_dwordx4 v223, s[44:47], s15 offen lds
	s_add_u32 m0, s18, 0x400
	s_nop 0
	buffer_load_dwordx4 v222, s[44:47], s15 offen lds
	s_add_u32 m0, s18, 0x800
	s_nop 0
	buffer_load_dwordx4 v221, s[44:47], s15 offen lds
	s_add_u32 m0, s18, 0xc00
	s_nop 0
	buffer_load_dwordx4 v220, s[44:47], s15 offen lds
	s_add_u32 m0, s18, 0x8000
	s_nop 0
	buffer_load_dwordx4 v219, s[44:47], s15 offen lds
	s_add_u32 m0, s18, 0x8400
	s_nop 0
	buffer_load_dwordx4 v218, s[44:47], s15 offen lds
	s_add_u32 m0, s18, 0x8800
	s_nop 0
	buffer_load_dwordx4 v217, s[44:47], s15 offen lds
	s_add_u32 m0, s18, 0x8c00
	s_nop 0
	buffer_load_dwordx4 v216, s[44:47], s15 offen lds
	s_movk_i32 s15, 0x80
	ds_read_b128 v[162:165], v252 offset:32768
	ds_read_b128 v[166:169], v252 offset:34816
	ds_read_b128 v[170:173], v252 offset:36864
	ds_read_b128 v[174:177], v252 offset:38912
	ds_read_b128 v[146:149], v250 offset:8192
	ds_read_b128 v[150:153], v250 offset:10240
	ds_read_b128 v[154:157], v250 offset:12288
	ds_read_b128 v[158:161], v250 offset:14336
	ds_read_b128 v[130:133], v250
	ds_read_b128 v[134:137], v250 offset:2048
	ds_read_b128 v[138:141], v250 offset:4096
	ds_read_b128 v[142:145], v250 offset:6144
	s_movk_i32 s19, 14
.Lp5_steady:
	s_waitcnt lgkmcnt(4)
	v_add_u32_e32 v248, s14, v251
	v_add_u32_e32 v249, s14, v253
	ds_read_b128 v[178:181], v249 offset:32768
	ds_read_b128 v[182:185], v249 offset:34816
	ds_read_b128 v[186:189], v249 offset:36864
	ds_read_b128 v[190:193], v249 offset:38912
	ds_read_b128 v[232:235], v248
	ds_read_b128 v[236:239], v248 offset:2048
	ds_read_b128 v[240:243], v248 offset:4096
	ds_read_b128 v[244:247], v248 offset:6144
	s_waitcnt lgkmcnt(8)
	v_mfma_f32_16x16x32_bf16 v[122:125], v[162:165], v[130:133], v[122:125]
	v_mfma_f32_16x16x32_bf16 v[114:117], v[166:169], v[130:133], v[114:117]
	v_mfma_f32_16x16x32_bf16 v[126:129], v[170:173], v[130:133], v[126:129]
	v_mfma_f32_16x16x32_bf16 v[118:121], v[174:177], v[130:133], v[118:121]
	v_mfma_f32_16x16x32_bf16 v[106:109], v[162:165], v[134:137], v[106:109]
	v_mfma_f32_16x16x32_bf16 v[98:101], v[166:169], v[134:137], v[98:101]
	v_mfma_f32_16x16x32_bf16 v[110:113], v[170:173], v[134:137], v[110:113]
	v_mfma_f32_16x16x32_bf16 v[102:105], v[174:177], v[134:137], v[102:105]
	v_mfma_f32_16x16x32_bf16 v[90:93], v[162:165], v[138:141], v[90:93]
	v_mfma_f32_16x16x32_bf16 v[82:85], v[166:169], v[138:141], v[82:85]
	v_mfma_f32_16x16x32_bf16 v[94:97], v[170:173], v[138:141], v[94:97]
	v_mfma_f32_16x16x32_bf16 v[86:89], v[174:177], v[138:141], v[86:89]
	v_mfma_f32_16x16x32_bf16 v[74:77], v[162:165], v[142:145], v[74:77]
	v_mfma_f32_16x16x32_bf16 v[66:69], v[166:169], v[142:145], v[66:69]
	v_mfma_f32_16x16x32_bf16 v[78:81], v[170:173], v[142:145], v[78:81]
	v_mfma_f32_16x16x32_bf16 v[70:73], v[174:177], v[142:145], v[70:73]
	ds_read_b128 v[130:133], v248 offset:8192
	ds_read_b128 v[134:137], v248 offset:10240
	ds_read_b128 v[138:141], v248 offset:12288
	ds_read_b128 v[142:145], v248 offset:14336
	v_mfma_f32_16x16x32_bf16 v[58:61], v[162:165], v[146:149], v[58:61]
	v_mfma_f32_16x16x32_bf16 v[50:53], v[166:169], v[146:149], v[50:53]
	v_mfma_f32_16x16x32_bf16 v[62:65], v[170:173], v[146:149], v[62:65]
	v_mfma_f32_16x16x32_bf16 v[54:57], v[174:177], v[146:149], v[54:57]
	v_mfma_f32_16x16x32_bf16 v[42:45], v[162:165], v[150:153], v[42:45]
	v_mfma_f32_16x16x32_bf16 v[30:33], v[166:169], v[150:153], v[30:33]
	v_mfma_f32_16x16x32_bf16 v[46:49], v[170:173], v[150:153], v[46:49]
	v_mfma_f32_16x16x32_bf16 v[38:41], v[174:177], v[150:153], v[38:41]
	v_mfma_f32_16x16x32_bf16 v[26:29], v[162:165], v[154:157], v[26:29]
	v_mfma_f32_16x16x32_bf16 v[14:17], v[166:169], v[154:157], v[14:17]
	v_mfma_f32_16x16x32_bf16 v[34:37], v[170:173], v[154:157], v[34:37]
	v_mfma_f32_16x16x32_bf16 v[22:25], v[174:177], v[154:157], v[22:25]
	v_mfma_f32_16x16x32_bf16 v[6:9], v[162:165], v[158:161], v[6:9]
	v_mfma_f32_16x16x32_bf16 v[2:5], v[166:169], v[158:161], v[2:5]
	v_mfma_f32_16x16x32_bf16 v[10:13], v[170:173], v[158:161], v[10:13]
	v_mfma_f32_16x16x32_bf16 v[18:21], v[174:177], v[158:161], v[18:21]
	s_waitcnt lgkmcnt(0)
	s_waitcnt vmcnt(0)
	s_barrier
	s_xor_b32 s17, s14, 0x10000
	s_add_i32 s18, s14, s16
	v_add_u32_e32 v248, s17, v250
	v_add_u32_e32 v249, s17, v252
	ds_read_b128 v[162:165], v249 offset:32768
	ds_read_b128 v[166:169], v249 offset:34816
	ds_read_b128 v[170:173], v249 offset:36864
	ds_read_b128 v[174:177], v249 offset:38912
	ds_read_b128 v[146:149], v248 offset:8192
	ds_read_b128 v[150:153], v248 offset:10240
	ds_read_b128 v[154:157], v248 offset:12288
	ds_read_b128 v[158:161], v248 offset:14336
	v_mfma_f32_16x16x32_bf16 v[58:61], v[178:181], v[130:133], v[58:61]
	s_mov_b32 m0, s18
	v_mfma_f32_16x16x32_bf16 v[50:53], v[182:185], v[130:133], v[50:53]
	buffer_load_dwordx4 v223, s[44:47], s15 offen lds
	v_mfma_f32_16x16x32_bf16 v[62:65], v[186:189], v[130:133], v[62:65]
	v_mfma_f32_16x16x32_bf16 v[54:57], v[190:193], v[130:133], v[54:57]
	v_mfma_f32_16x16x32_bf16 v[42:45], v[178:181], v[134:137], v[42:45]
	s_add_u32 m0, s18, 0x400
	v_mfma_f32_16x16x32_bf16 v[30:33], v[182:185], v[134:137], v[30:33]
	buffer_load_dwordx4 v222, s[44:47], s15 offen lds
	v_mfma_f32_16x16x32_bf16 v[46:49], v[186:189], v[134:137], v[46:49]
	v_mfma_f32_16x16x32_bf16 v[38:41], v[190:193], v[134:137], v[38:41]
	v_mfma_f32_16x16x32_bf16 v[26:29], v[178:181], v[138:141], v[26:29]
	s_add_u32 m0, s18, 0x800
	v_mfma_f32_16x16x32_bf16 v[14:17], v[182:185], v[138:141], v[14:17]
	buffer_load_dwordx4 v221, s[44:47], s15 offen lds
	v_mfma_f32_16x16x32_bf16 v[34:37], v[186:189], v[138:141], v[34:37]
	v_mfma_f32_16x16x32_bf16 v[22:25], v[190:193], v[138:141], v[22:25]
	v_mfma_f32_16x16x32_bf16 v[6:9], v[178:181], v[142:145], v[6:9]
	s_add_u32 m0, s18, 0xc00
	v_mfma_f32_16x16x32_bf16 v[2:5], v[182:185], v[142:145], v[2:5]
	buffer_load_dwordx4 v220, s[44:47], s15 offen lds
	v_mfma_f32_16x16x32_bf16 v[10:13], v[186:189], v[142:145], v[10:13]
	v_mfma_f32_16x16x32_bf16 v[18:21], v[190:193], v[142:145], v[18:21]
	ds_read_b128 v[130:133], v248
	ds_read_b128 v[134:137], v248 offset:2048
	ds_read_b128 v[138:141], v248 offset:4096
	ds_read_b128 v[142:145], v248 offset:6144
	v_mfma_f32_16x16x32_bf16 v[122:125], v[178:181], v[232:235], v[122:125]
	s_add_u32 m0, s18, 0x8000
	v_mfma_f32_16x16x32_bf16 v[114:117], v[182:185], v[232:235], v[114:117]
	buffer_load_dwordx4 v219, s[44:47], s15 offen lds
	v_mfma_f32_16x16x32_bf16 v[126:129], v[186:189], v[232:235], v[126:129]
	v_mfma_f32_16x16x32_bf16 v[118:121], v[190:193], v[232:235], v[118:121]
	v_mfma_f32_16x16x32_bf16 v[106:109], v[178:181], v[236:239], v[106:109]
	s_add_u32 m0, s18, 0x8400
	v_mfma_f32_16x16x32_bf16 v[98:101], v[182:185], v[236:239], v[98:101]
	buffer_load_dwordx4 v218, s[44:47], s15 offen lds
	v_mfma_f32_16x16x32_bf16 v[110:113], v[186:189], v[236:239], v[110:113]
	v_mfma_f32_16x16x32_bf16 v[102:105], v[190:193], v[236:239], v[102:105]
	v_mfma_f32_16x16x32_bf16 v[90:93], v[178:181], v[240:243], v[90:93]
	s_add_u32 m0, s18, 0x8800
	v_mfma_f32_16x16x32_bf16 v[82:85], v[182:185], v[240:243], v[82:85]
	buffer_load_dwordx4 v217, s[44:47], s15 offen lds
	v_mfma_f32_16x16x32_bf16 v[94:97], v[186:189], v[240:243], v[94:97]
	v_mfma_f32_16x16x32_bf16 v[86:89], v[190:193], v[240:243], v[86:89]
	v_mfma_f32_16x16x32_bf16 v[74:77], v[178:181], v[244:247], v[74:77]
	s_add_u32 m0, s18, 0x8c00
	v_mfma_f32_16x16x32_bf16 v[66:69], v[182:185], v[244:247], v[66:69]
	buffer_load_dwordx4 v216, s[44:47], s15 offen lds
	v_mfma_f32_16x16x32_bf16 v[78:81], v[186:189], v[244:247], v[78:81]
	v_mfma_f32_16x16x32_bf16 v[70:73], v[190:193], v[244:247], v[70:73]
	s_xor_b32 s14, s14, 0x10000
	s_addk_i32 s15, 0x80
	s_add_i32 s19, s19, -1
	s_cmp_lg_u32 s19, 0
	s_cbranch_scc1 .Lp5_steady
	s_waitcnt lgkmcnt(4)
	v_add_u32_e32 v248, s14, v251
	v_add_u32_e32 v249, s14, v253
	ds_read_b128 v[178:181], v249 offset:32768
	ds_read_b128 v[182:185], v249 offset:34816
	ds_read_b128 v[186:189], v249 offset:36864
	ds_read_b128 v[190:193], v249 offset:38912
	ds_read_b128 v[232:235], v248
	ds_read_b128 v[236:239], v248 offset:2048
	ds_read_b128 v[240:243], v248 offset:4096
	ds_read_b128 v[244:247], v248 offset:6144
	s_waitcnt lgkmcnt(8)
	v_mfma_f32_16x16x32_bf16 v[122:125], v[162:165], v[130:133], v[122:125]
	v_mfma_f32_16x16x32_bf16 v[114:117], v[166:169], v[130:133], v[114:117]
	v_mfma_f32_16x16x32_bf16 v[126:129], v[170:173], v[130:133], v[126:129]
	v_mfma_f32_16x16x32_bf16 v[118:121], v[174:177], v[130:133], v[118:121]
	v_mfma_f32_16x16x32_bf16 v[106:109], v[162:165], v[134:137], v[106:109]
	v_mfma_f32_16x16x32_bf16 v[98:101], v[166:169], v[134:137], v[98:101]
	v_mfma_f32_16x16x32_bf16 v[110:113], v[170:173], v[134:137], v[110:113]
	v_mfma_f32_16x16x32_bf16 v[102:105], v[174:177], v[134:137], v[102:105]
	v_mfma_f32_16x16x32_bf16 v[90:93], v[162:165], v[138:141], v[90:93]
	v_mfma_f32_16x16x32_bf16 v[82:85], v[166:169], v[138:141], v[82:85]
	v_mfma_f32_16x16x32_bf16 v[94:97], v[170:173], v[138:141], v[94:97]
	v_mfma_f32_16x16x32_bf16 v[86:89], v[174:177], v[138:141], v[86:89]
	v_mfma_f32_16x16x32_bf16 v[74:77], v[162:165], v[142:145], v[74:77]
	v_mfma_f32_16x16x32_bf16 v[66:69], v[166:169], v[142:145], v[66:69]
	v_mfma_f32_16x16x32_bf16 v[78:81], v[170:173], v[142:145], v[78:81]
	v_mfma_f32_16x16x32_bf16 v[70:73], v[174:177], v[142:145], v[70:73]
	ds_read_b128 v[130:133], v248 offset:8192
	ds_read_b128 v[134:137], v248 offset:10240
	ds_read_b128 v[138:141], v248 offset:12288
	ds_read_b128 v[142:145], v248 offset:14336
	v_mfma_f32_16x16x32_bf16 v[58:61], v[162:165], v[146:149], v[58:61]
	v_mfma_f32_16x16x32_bf16 v[50:53], v[166:169], v[146:149], v[50:53]
	v_mfma_f32_16x16x32_bf16 v[62:65], v[170:173], v[146:149], v[62:65]
	v_mfma_f32_16x16x32_bf16 v[54:57], v[174:177], v[146:149], v[54:57]
	v_mfma_f32_16x16x32_bf16 v[42:45], v[162:165], v[150:153], v[42:45]
	v_mfma_f32_16x16x32_bf16 v[30:33], v[166:169], v[150:153], v[30:33]
	v_mfma_f32_16x16x32_bf16 v[46:49], v[170:173], v[150:153], v[46:49]
	v_mfma_f32_16x16x32_bf16 v[38:41], v[174:177], v[150:153], v[38:41]
	v_mfma_f32_16x16x32_bf16 v[26:29], v[162:165], v[154:157], v[26:29]
	v_mfma_f32_16x16x32_bf16 v[14:17], v[166:169], v[154:157], v[14:17]
	v_mfma_f32_16x16x32_bf16 v[34:37], v[170:173], v[154:157], v[34:37]
	v_mfma_f32_16x16x32_bf16 v[22:25], v[174:177], v[154:157], v[22:25]
	v_mfma_f32_16x16x32_bf16 v[6:9], v[162:165], v[158:161], v[6:9]
	v_mfma_f32_16x16x32_bf16 v[2:5], v[166:169], v[158:161], v[2:5]
	v_mfma_f32_16x16x32_bf16 v[10:13], v[170:173], v[158:161], v[10:13]
	v_mfma_f32_16x16x32_bf16 v[18:21], v[174:177], v[158:161], v[18:21]
	s_waitcnt lgkmcnt(0)
	s_waitcnt vmcnt(0)
	s_barrier
	s_xor_b32 s17, s14, 0x10000
	v_add_u32_e32 v248, s17, v250
	v_add_u32_e32 v249, s17, v252
	ds_read_b128 v[162:165], v249 offset:32768
	ds_read_b128 v[166:169], v249 offset:34816
	ds_read_b128 v[170:173], v249 offset:36864
	ds_read_b128 v[174:177], v249 offset:38912
	ds_read_b128 v[146:149], v248 offset:8192
	ds_read_b128 v[150:153], v248 offset:10240
	ds_read_b128 v[154:157], v248 offset:12288
	ds_read_b128 v[158:161], v248 offset:14336
	v_mfma_f32_16x16x32_bf16 v[58:61], v[178:181], v[130:133], v[58:61]
	v_mfma_f32_16x16x32_bf16 v[50:53], v[182:185], v[130:133], v[50:53]
	v_mfma_f32_16x16x32_bf16 v[62:65], v[186:189], v[130:133], v[62:65]
	v_mfma_f32_16x16x32_bf16 v[54:57], v[190:193], v[130:133], v[54:57]
	v_mfma_f32_16x16x32_bf16 v[42:45], v[178:181], v[134:137], v[42:45]
	v_mfma_f32_16x16x32_bf16 v[30:33], v[182:185], v[134:137], v[30:33]
	v_mfma_f32_16x16x32_bf16 v[46:49], v[186:189], v[134:137], v[46:49]
	v_mfma_f32_16x16x32_bf16 v[38:41], v[190:193], v[134:137], v[38:41]
	v_mfma_f32_16x16x32_bf16 v[26:29], v[178:181], v[138:141], v[26:29]
	v_mfma_f32_16x16x32_bf16 v[14:17], v[182:185], v[138:141], v[14:17]
	v_mfma_f32_16x16x32_bf16 v[34:37], v[186:189], v[138:141], v[34:37]
	v_mfma_f32_16x16x32_bf16 v[22:25], v[190:193], v[138:141], v[22:25]
	v_mfma_f32_16x16x32_bf16 v[6:9], v[178:181], v[142:145], v[6:9]
	v_mfma_f32_16x16x32_bf16 v[2:5], v[182:185], v[142:145], v[2:5]
	v_mfma_f32_16x16x32_bf16 v[10:13], v[186:189], v[142:145], v[10:13]
	v_mfma_f32_16x16x32_bf16 v[18:21], v[190:193], v[142:145], v[18:21]
	ds_read_b128 v[130:133], v248
	ds_read_b128 v[134:137], v248 offset:2048
	ds_read_b128 v[138:141], v248 offset:4096
	ds_read_b128 v[142:145], v248 offset:6144
	v_mfma_f32_16x16x32_bf16 v[122:125], v[178:181], v[232:235], v[122:125]
	v_mfma_f32_16x16x32_bf16 v[114:117], v[182:185], v[232:235], v[114:117]
	v_mfma_f32_16x16x32_bf16 v[126:129], v[186:189], v[232:235], v[126:129]
	v_mfma_f32_16x16x32_bf16 v[118:121], v[190:193], v[232:235], v[118:121]
	v_mfma_f32_16x16x32_bf16 v[106:109], v[178:181], v[236:239], v[106:109]
	v_mfma_f32_16x16x32_bf16 v[98:101], v[182:185], v[236:239], v[98:101]
	v_mfma_f32_16x16x32_bf16 v[110:113], v[186:189], v[236:239], v[110:113]
	v_mfma_f32_16x16x32_bf16 v[102:105], v[190:193], v[236:239], v[102:105]
	v_mfma_f32_16x16x32_bf16 v[90:93], v[178:181], v[240:243], v[90:93]
	v_mfma_f32_16x16x32_bf16 v[82:85], v[182:185], v[240:243], v[82:85]
	v_mfma_f32_16x16x32_bf16 v[94:97], v[186:189], v[240:243], v[94:97]
	v_mfma_f32_16x16x32_bf16 v[86:89], v[190:193], v[240:243], v[86:89]
	v_mfma_f32_16x16x32_bf16 v[74:77], v[178:181], v[244:247], v[74:77]
	v_mfma_f32_16x16x32_bf16 v[66:69], v[182:185], v[244:247], v[66:69]
	v_mfma_f32_16x16x32_bf16 v[78:81], v[186:189], v[244:247], v[78:81]
	v_mfma_f32_16x16x32_bf16 v[70:73], v[190:193], v[244:247], v[70:73]
	s_xor_b32 s14, s14, 0x10000
	s_waitcnt lgkmcnt(4)
	v_add_u32_e32 v248, s14, v251
	v_add_u32_e32 v249, s14, v253
	ds_read_b128 v[178:181], v249 offset:32768
	ds_read_b128 v[182:185], v249 offset:34816
	ds_read_b128 v[186:189], v249 offset:36864
	ds_read_b128 v[190:193], v249 offset:38912
	ds_read_b128 v[232:235], v248
	ds_read_b128 v[236:239], v248 offset:2048
	ds_read_b128 v[240:243], v248 offset:4096
	ds_read_b128 v[244:247], v248 offset:6144
	s_waitcnt lgkmcnt(8)
	v_mfma_f32_16x16x32_bf16 v[122:125], v[162:165], v[130:133], v[122:125]
	v_mfma_f32_16x16x32_bf16 v[114:117], v[166:169], v[130:133], v[114:117]
	v_mfma_f32_16x16x32_bf16 v[126:129], v[170:173], v[130:133], v[126:129]
	v_mfma_f32_16x16x32_bf16 v[118:121], v[174:177], v[130:133], v[118:121]
	v_mfma_f32_16x16x32_bf16 v[106:109], v[162:165], v[134:137], v[106:109]
	v_mfma_f32_16x16x32_bf16 v[98:101], v[166:169], v[134:137], v[98:101]
	v_mfma_f32_16x16x32_bf16 v[110:113], v[170:173], v[134:137], v[110:113]
	v_mfma_f32_16x16x32_bf16 v[102:105], v[174:177], v[134:137], v[102:105]
	v_mfma_f32_16x16x32_bf16 v[90:93], v[162:165], v[138:141], v[90:93]
	v_mfma_f32_16x16x32_bf16 v[82:85], v[166:169], v[138:141], v[82:85]
	v_mfma_f32_16x16x32_bf16 v[94:97], v[170:173], v[138:141], v[94:97]
	v_mfma_f32_16x16x32_bf16 v[86:89], v[174:177], v[138:141], v[86:89]
	v_mfma_f32_16x16x32_bf16 v[74:77], v[162:165], v[142:145], v[74:77]
	v_mfma_f32_16x16x32_bf16 v[66:69], v[166:169], v[142:145], v[66:69]
	v_mfma_f32_16x16x32_bf16 v[78:81], v[170:173], v[142:145], v[78:81]
	v_mfma_f32_16x16x32_bf16 v[70:73], v[174:177], v[142:145], v[70:73]
	ds_read_b128 v[130:133], v248 offset:8192
	ds_read_b128 v[134:137], v248 offset:10240
	ds_read_b128 v[138:141], v248 offset:12288
	ds_read_b128 v[142:145], v248 offset:14336
	v_mfma_f32_16x16x32_bf16 v[58:61], v[162:165], v[146:149], v[58:61]
	v_mfma_f32_16x16x32_bf16 v[50:53], v[166:169], v[146:149], v[50:53]
	v_mfma_f32_16x16x32_bf16 v[62:65], v[170:173], v[146:149], v[62:65]
	v_mfma_f32_16x16x32_bf16 v[54:57], v[174:177], v[146:149], v[54:57]
	v_mfma_f32_16x16x32_bf16 v[42:45], v[162:165], v[150:153], v[42:45]
	v_mfma_f32_16x16x32_bf16 v[30:33], v[166:169], v[150:153], v[30:33]
	v_mfma_f32_16x16x32_bf16 v[46:49], v[170:173], v[150:153], v[46:49]
	v_mfma_f32_16x16x32_bf16 v[38:41], v[174:177], v[150:153], v[38:41]
	v_mfma_f32_16x16x32_bf16 v[26:29], v[162:165], v[154:157], v[26:29]
	v_mfma_f32_16x16x32_bf16 v[14:17], v[166:169], v[154:157], v[14:17]
	v_mfma_f32_16x16x32_bf16 v[34:37], v[170:173], v[154:157], v[34:37]
	v_mfma_f32_16x16x32_bf16 v[22:25], v[174:177], v[154:157], v[22:25]
	v_mfma_f32_16x16x32_bf16 v[6:9], v[162:165], v[158:161], v[6:9]
	v_mfma_f32_16x16x32_bf16 v[2:5], v[166:169], v[158:161], v[2:5]
	v_mfma_f32_16x16x32_bf16 v[10:13], v[170:173], v[158:161], v[10:13]
	v_mfma_f32_16x16x32_bf16 v[18:21], v[174:177], v[158:161], v[18:21]
	s_waitcnt lgkmcnt(0)
	v_mfma_f32_16x16x32_bf16 v[58:61], v[178:181], v[130:133], v[58:61]
	v_mfma_f32_16x16x32_bf16 v[50:53], v[182:185], v[130:133], v[50:53]
	v_mfma_f32_16x16x32_bf16 v[62:65], v[186:189], v[130:133], v[62:65]
	v_mfma_f32_16x16x32_bf16 v[54:57], v[190:193], v[130:133], v[54:57]
	v_mfma_f32_16x16x32_bf16 v[42:45], v[178:181], v[134:137], v[42:45]
	v_mfma_f32_16x16x32_bf16 v[30:33], v[182:185], v[134:137], v[30:33]
	v_mfma_f32_16x16x32_bf16 v[46:49], v[186:189], v[134:137], v[46:49]
	v_mfma_f32_16x16x32_bf16 v[38:41], v[190:193], v[134:137], v[38:41]
	v_mfma_f32_16x16x32_bf16 v[26:29], v[178:181], v[138:141], v[26:29]
	v_mfma_f32_16x16x32_bf16 v[14:17], v[182:185], v[138:141], v[14:17]
	v_mfma_f32_16x16x32_bf16 v[34:37], v[186:189], v[138:141], v[34:37]
	v_mfma_f32_16x16x32_bf16 v[22:25], v[190:193], v[138:141], v[22:25]
	v_mfma_f32_16x16x32_bf16 v[6:9], v[178:181], v[142:145], v[6:9]
	v_mfma_f32_16x16x32_bf16 v[2:5], v[182:185], v[142:145], v[2:5]
	v_mfma_f32_16x16x32_bf16 v[10:13], v[186:189], v[142:145], v[10:13]
	v_mfma_f32_16x16x32_bf16 v[18:21], v[190:193], v[142:145], v[18:21]
	v_mfma_f32_16x16x32_bf16 v[122:125], v[178:181], v[232:235], v[122:125]
	v_mfma_f32_16x16x32_bf16 v[114:117], v[182:185], v[232:235], v[114:117]
	v_mfma_f32_16x16x32_bf16 v[126:129], v[186:189], v[232:235], v[126:129]
	v_mfma_f32_16x16x32_bf16 v[118:121], v[190:193], v[232:235], v[118:121]
	v_mfma_f32_16x16x32_bf16 v[106:109], v[178:181], v[236:239], v[106:109]
	v_mfma_f32_16x16x32_bf16 v[98:101], v[182:185], v[236:239], v[98:101]
	v_mfma_f32_16x16x32_bf16 v[110:113], v[186:189], v[236:239], v[110:113]
	v_mfma_f32_16x16x32_bf16 v[102:105], v[190:193], v[236:239], v[102:105]
	v_mfma_f32_16x16x32_bf16 v[90:93], v[178:181], v[240:243], v[90:93]
	v_mfma_f32_16x16x32_bf16 v[82:85], v[182:185], v[240:243], v[82:85]
	v_mfma_f32_16x16x32_bf16 v[94:97], v[186:189], v[240:243], v[94:97]
	v_mfma_f32_16x16x32_bf16 v[86:89], v[190:193], v[240:243], v[86:89]
	v_mfma_f32_16x16x32_bf16 v[74:77], v[178:181], v[244:247], v[74:77]
	v_mfma_f32_16x16x32_bf16 v[66:69], v[182:185], v[244:247], v[66:69]
	v_mfma_f32_16x16x32_bf16 v[78:81], v[186:189], v[244:247], v[78:81]
	v_mfma_f32_16x16x32_bf16 v[70:73], v[190:193], v[244:247], v[70:73]
	s_branch .LBB0_797

.LBB0_870:
	v_and_b32_e32 v130, 63, v194
	v_lshrrev_b32_e32 v134, 6, v194
	v_lshrrev_b32_e32 v131, 3, v130
	v_and_b32_e32 v132, 7, v130
	v_xor_b32_e32 v133, v132, v131
	v_lshlrev_b32_e32 v133, 4, v133
	v_lshl_add_u32 v135, v131, 7, v133
	v_lshl_add_u32 v135, v134, 11, v135
	v_add_u32_e32 v135, 0x20000, v135
	v_and_b32_e32 v138, 15, v130
	v_lshrrev_b32_e32 v137, 4, v130
	v_lshrrev_b32_e32 v133, 1, v137
	v_bitop3_b32 v133, v133, v138, 7 bitop3:0x78
	v_lshlrev_b32_e32 v133, 4, v133
	v_lshl_add_u32 v136, v138, 7, v133
	v_and_b32_e32 v133, 1, v137
	v_lshl_add_u32 v136, v133, 3, v136
	v_lshl_add_u32 v136, v134, 11, v136
	v_add_u32_e32 v136, 0x20000, v136
	v_lshl_add_u32 v139, v212, 7, v131
	v_lshlrev_b32_e32 v139, 12, v139
	v_lshl_add_u32 v139, v204, 7, v139
	v_lshl_add_u32 v139, v132, 4, v139
	s_sub_u32 s12, s98, s44
	s_lshl_b32 s14, s4, 20
	s_add_u32 s12, s12, s14
	s_lshl_b32 s14, s28, 9
	s_add_u32 s12, s12, s14
	v_cvt_pk_bf16_f32 v140, v126, v127
	v_cvt_pk_bf16_f32 v141, v128, v129
	v_cvt_pk_bf16_f32 v142, v122, v123
	v_cvt_pk_bf16_f32 v143, v124, v125
	v_cvt_pk_bf16_f32 v144, v118, v119
	v_cvt_pk_bf16_f32 v145, v120, v121
	v_cvt_pk_bf16_f32 v146, v114, v115
	v_cvt_pk_bf16_f32 v147, v116, v117
	ds_write_b64 v136, v[140:141]
	v_xor_b32_e32 v173, 0x20, v136
	ds_write_b64 v173, v[142:143]
	v_xor_b32_e32 v174, 0x40, v136
	ds_write_b64 v174, v[144:145]
	v_xor_b32_e32 v175, 0x60, v136
	ds_write_b64 v175, v[146:147]
	ds_read_b128 v[148:151], v135
	ds_read_b128 v[152:155], v135 offset:1024
	v_cvt_pk_bf16_f32 v164, v110, v111
	v_cvt_pk_bf16_f32 v165, v112, v113
	v_cvt_pk_bf16_f32 v166, v106, v107
	v_cvt_pk_bf16_f32 v167, v108, v109
	v_cvt_pk_bf16_f32 v168, v102, v103
	v_cvt_pk_bf16_f32 v169, v104, v105
	v_cvt_pk_bf16_f32 v170, v98, v99
	v_cvt_pk_bf16_f32 v171, v100, v101
	ds_write_b64 v136, v[164:165]
	v_xor_b32_e32 v173, 0x20, v136
	ds_write_b64 v173, v[166:167]
	v_xor_b32_e32 v174, 0x40, v136
	ds_write_b64 v174, v[168:169]
	v_xor_b32_e32 v175, 0x60, v136
	ds_write_b64 v175, v[170:171]
	ds_read_b128 v[156:159], v135
	ds_read_b128 v[160:163], v135 offset:1024
	s_waitcnt lgkmcnt(6)
	buffer_store_dwordx4 v[148:151], v139, s[44:47], s12 offen
	s_add_u32 s12, s12, 0x8000
	buffer_store_dwordx4 v[152:155], v139, s[44:47], s12 offen
	s_add_u32 s12, s12, 0x8000
	v_cvt_pk_bf16_f32 v140, v94, v95
	v_cvt_pk_bf16_f32 v141, v96, v97
	v_cvt_pk_bf16_f32 v142, v90, v91
	v_cvt_pk_bf16_f32 v143, v92, v93
	v_cvt_pk_bf16_f32 v144, v86, v87
	v_cvt_pk_bf16_f32 v145, v88, v89
	v_cvt_pk_bf16_f32 v146, v82, v83
	v_cvt_pk_bf16_f32 v147, v84, v85
	ds_write_b64 v136, v[140:141]
	v_xor_b32_e32 v173, 0x20, v136
	ds_write_b64 v173, v[142:143]
	v_xor_b32_e32 v174, 0x40, v136
	ds_write_b64 v174, v[144:145]
	v_xor_b32_e32 v175, 0x60, v136
	ds_write_b64 v175, v[146:147]
	ds_read_b128 v[148:151], v135
	ds_read_b128 v[152:155], v135 offset:1024
	s_waitcnt lgkmcnt(6)
	buffer_store_dwordx4 v[156:159], v139, s[44:47], s12 offen
	s_add_u32 s12, s12, 0x8000
	buffer_store_dwordx4 v[160:163], v139, s[44:47], s12 offen
	s_add_u32 s12, s12, 0x8000
	v_cvt_pk_bf16_f32 v164, v78, v79
	v_cvt_pk_bf16_f32 v165, v80, v81
	v_cvt_pk_bf16_f32 v166, v74, v75
	v_cvt_pk_bf16_f32 v167, v76, v77
	v_cvt_pk_bf16_f32 v168, v70, v71
	v_cvt_pk_bf16_f32 v169, v72, v73
	v_cvt_pk_bf16_f32 v170, v66, v67
	v_cvt_pk_bf16_f32 v171, v68, v69
	ds_write_b64 v136, v[164:165]
	v_xor_b32_e32 v173, 0x20, v136
	ds_write_b64 v173, v[166:167]
	v_xor_b32_e32 v174, 0x40, v136
	ds_write_b64 v174, v[168:169]
	v_xor_b32_e32 v175, 0x60, v136
	ds_write_b64 v175, v[170:171]
	ds_read_b128 v[156:159], v135
	ds_read_b128 v[160:163], v135 offset:1024
	s_waitcnt lgkmcnt(6)
	buffer_store_dwordx4 v[148:151], v139, s[44:47], s12 offen
	s_add_u32 s12, s12, 0x8000
	buffer_store_dwordx4 v[152:155], v139, s[44:47], s12 offen
	s_add_u32 s12, s12, 0x8000
	v_cvt_pk_bf16_f32 v140, v58, v59
	v_cvt_pk_bf16_f32 v141, v60, v61
	v_cvt_pk_bf16_f32 v142, v54, v55
	v_cvt_pk_bf16_f32 v143, v56, v57
	v_cvt_pk_bf16_f32 v144, v50, v51
	v_cvt_pk_bf16_f32 v145, v52, v53
	v_cvt_pk_bf16_f32 v146, v46, v47
	v_cvt_pk_bf16_f32 v147, v48, v49
	ds_write_b64 v136, v[140:141]
	v_xor_b32_e32 v173, 0x20, v136
	ds_write_b64 v173, v[142:143]
	v_xor_b32_e32 v174, 0x40, v136
	ds_write_b64 v174, v[144:145]
	v_xor_b32_e32 v175, 0x60, v136
	ds_write_b64 v175, v[146:147]
	ds_read_b128 v[148:151], v135
	ds_read_b128 v[152:155], v135 offset:1024
	s_waitcnt lgkmcnt(6)
	buffer_store_dwordx4 v[156:159], v139, s[44:47], s12 offen
	s_add_u32 s12, s12, 0x8000
	buffer_store_dwordx4 v[160:163], v139, s[44:47], s12 offen
	s_add_u32 s12, s12, 0x8000
	v_cvt_pk_bf16_f32 v164, v26, v27
	v_cvt_pk_bf16_f32 v165, v28, v29
	v_cvt_pk_bf16_f32 v166, v22, v23
	v_cvt_pk_bf16_f32 v167, v24, v25
	v_cvt_pk_bf16_f32 v168, v14, v15
	v_cvt_pk_bf16_f32 v169, v16, v17
	v_cvt_pk_bf16_f32 v170, v2, v3
	v_cvt_pk_bf16_f32 v171, v4, v5
	ds_write_b64 v136, v[164:165]
	v_xor_b32_e32 v173, 0x20, v136
	ds_write_b64 v173, v[166:167]
	v_xor_b32_e32 v174, 0x40, v136
	ds_write_b64 v174, v[168:169]
	v_xor_b32_e32 v175, 0x60, v136
	ds_write_b64 v175, v[170:171]
	ds_read_b128 v[156:159], v135
	ds_read_b128 v[160:163], v135 offset:1024
	s_waitcnt lgkmcnt(6)
	buffer_store_dwordx4 v[148:151], v139, s[44:47], s12 offen
	s_add_u32 s12, s12, 0x8000
	buffer_store_dwordx4 v[152:155], v139, s[44:47], s12 offen
	s_add_u32 s12, s12, 0x8000
	v_cvt_pk_bf16_f32 v140, v42, v43
	v_cvt_pk_bf16_f32 v141, v44, v45
	v_cvt_pk_bf16_f32 v142, v38, v39
	v_cvt_pk_bf16_f32 v143, v40, v41
	v_cvt_pk_bf16_f32 v144, v34, v35
	v_cvt_pk_bf16_f32 v145, v36, v37
	v_cvt_pk_bf16_f32 v146, v30, v31
	v_cvt_pk_bf16_f32 v147, v32, v33
	ds_write_b64 v136, v[140:141]
	v_xor_b32_e32 v173, 0x20, v136
	ds_write_b64 v173, v[142:143]
	v_xor_b32_e32 v174, 0x40, v136
	ds_write_b64 v174, v[144:145]
	v_xor_b32_e32 v175, 0x60, v136
	ds_write_b64 v175, v[146:147]
	ds_read_b128 v[148:151], v135
	ds_read_b128 v[152:155], v135 offset:1024
	s_waitcnt lgkmcnt(6)
	buffer_store_dwordx4 v[156:159], v139, s[44:47], s12 offen
	s_add_u32 s12, s12, 0x8000
	buffer_store_dwordx4 v[160:163], v139, s[44:47], s12 offen
	s_add_u32 s12, s12, 0x8000
	v_cvt_pk_bf16_f32 v164, v18, v19
	v_cvt_pk_bf16_f32 v165, v20, v21
	v_cvt_pk_bf16_f32 v166, v10, v11
	v_cvt_pk_bf16_f32 v167, v12, v13
	v_cvt_pk_bf16_f32 v168, v6, v7
	v_cvt_pk_bf16_f32 v169, v8, v9
	v_cvt_pk_bf16_f32 v170, v62, v63
	v_cvt_pk_bf16_f32 v171, v64, v65
	ds_write_b64 v136, v[164:165]
	v_xor_b32_e32 v173, 0x20, v136
	ds_write_b64 v173, v[166:167]
	v_xor_b32_e32 v174, 0x40, v136
	ds_write_b64 v174, v[168:169]
	v_xor_b32_e32 v175, 0x60, v136
	ds_write_b64 v175, v[170:171]
	ds_read_b128 v[156:159], v135
	ds_read_b128 v[160:163], v135 offset:1024
	s_waitcnt lgkmcnt(6)
	buffer_store_dwordx4 v[148:151], v139, s[44:47], s12 offen
	s_add_u32 s12, s12, 0x8000
	buffer_store_dwordx4 v[152:155], v139, s[44:47], s12 offen
	s_add_u32 s12, s12, 0x8000
	s_waitcnt lgkmcnt(0)
	buffer_store_dwordx4 v[156:159], v139, s[44:47], s12 offen
	s_add_u32 s12, s12, 0x8000
	buffer_store_dwordx4 v[160:163], v139, s[44:47], s12 offen
	v_readlane_b32 s0, v229, 39
	s_add_i32 s27, s27, s34
	s_add_i32 s13, s13, s0
	s_cmpk_gt_i32 s27, 0x1ff
	s_barrier
	s_cbranch_scc1 .LBB0_889
.LBB0_871:
	s_bfe_u32 s4, s13, 0x20003
	s_ashr_i32 s36, s27, 3
	s_lshl_b32 s5, s27, 2
	s_lshl_b32 s7, s4, 23
	s_lshl_b32 s35, s4, 3
	s_and_b32 s37, s36, 0xffffffe0
	s_and_b32 s4, s5, 24
	s_bfe_u32 s30, s27, 0x30003
	s_or_b32 s4, s37, s4
	v_readlane_b32 s60, v230, 18
	s_bfe_u32 s1, s27, 0x20006
	s_or_b32 s4, s4, s30
	s_and_b32 s5, s5, 4
	v_readlane_b32 s61, v230, 19
	v_readlane_b32 s62, v230, 20
	v_readlane_b32 s68, v230, 26
	v_readlane_b32 s69, v230, 27
	v_mov_b32_e32 v2, v194
	s_lshl_b32 s6, s1, 20
	s_or_b32 s28, s5, s1
	s_lshl_b32 s1, s4, 20
	v_readlane_b32 s70, v230, 28
	s_mov_b64 s[60:61], s[68:69]
	s_movk_i32 s12, 0x70
	v_ashrrev_i32_e32 v3, 6, v2
	v_bfe_u32 v4, v2, 3, 3
	v_lshlrev_b32_e32 v8, 4, v2
	v_and_b32_e32 v9, 48, v2
	s_add_i32 s1, s94, s1
	s_mov_b32 s62, s70
	v_and_b32_e32 v204, 3, v3
	v_lshlrev_b32_e32 v7, 2, v3
	v_lshlrev_b32_e32 v208, 12, v3
	v_bitop3_b32 v8, v8, v9, s12 bitop3:0x6c
	v_lshlrev_b32_e32 v3, 17, v3
	v_lshlrev_b32_e32 v9, 12, v4
	s_sub_i32 s1, s1, s62
	v_or_b32_e32 v10, v9, v3
	v_readfirstlane_b32 s51, v208
	v_add3_u32 v11, v8, s1, v10
	s_mov_b32 m0, s51
	s_lshl_b32 s29, s28, 20
	buffer_load_dwordx4 v11, s[44:47], 0 offen lds
	v_or_b32_e32 v11, 1, v7
	v_lshl_or_b32 v12, v11, 3, v4
	v_lshrrev_b32_e32 v13, 1, v12
	v_xor_b32_e32 v13, v13, v2
	v_lshlrev_b32_e32 v209, 10, v11
	v_lshlrev_b32_e32 v11, 4, v13
	v_and_b32_e32 v11, 0x70, v11
	v_lshl_or_b32 v12, v12, 12, v11
	v_readfirstlane_b32 s51, v209
	v_add_u32_e32 v13, s1, v12
	s_mov_b32 m0, s51
	s_add_i32 s29, s2, s29
	buffer_load_dwordx4 v13, s[44:47], 0 offen lds
	v_or_b32_e32 v13, 2, v7
	v_lshl_or_b32 v14, v13, 3, v4
	v_lshrrev_b32_e32 v15, 1, v14
	v_xor_b32_e32 v15, v15, v2
	v_lshlrev_b32_e32 v210, 10, v13
	v_lshlrev_b32_e32 v13, 4, v15
	v_and_b32_e32 v13, 0x70, v13
	v_lshl_or_b32 v14, v14, 12, v13
	v_readfirstlane_b32 s51, v210
	v_or_b32_e32 v7, 3, v7
	v_add_u32_e32 v15, s1, v14
	s_mov_b32 m0, s51
	v_lshl_or_b32 v4, v7, 3, v4
	buffer_load_dwordx4 v15, s[44:47], 0 offen lds
	v_lshrrev_b32_e32 v15, 1, v4
	v_xor_b32_e32 v15, v15, v2
	v_lshlrev_b32_e32 v211, 10, v7
	v_lshlrev_b32_e32 v7, 4, v15
	v_and_b32_e32 v7, 0x70, v7
	v_lshl_or_b32 v4, v4, 12, v7
	v_add_u32_e32 v15, s1, v4
	v_readfirstlane_b32 s1, v211
	s_mov_b32 m0, s1
	s_sub_i32 s50, s29, s62
	buffer_load_dwordx4 v15, s[44:47], 0 offen lds
	v_add_u32_e32 v15, 0x8000, v208
	v_add3_u32 v10, v8, s50, v10
	v_readfirstlane_b32 s1, v15
	s_mov_b32 m0, s1
	v_add_u32_e32 v12, s50, v12
	buffer_load_dwordx4 v10, s[44:47], 0 offen lds
	v_add_u32_e32 v10, 0x8000, v209
	v_add_u32_e32 v4, s50, v4
	v_readfirstlane_b32 s1, v10
	v_add_u32_e32 v10, 0x8000, v210
	s_mov_b32 m0, s1
	v_readfirstlane_b32 s1, v10
	v_add_u32_e32 v10, 0x8000, v211
	buffer_load_dwordx4 v12, s[44:47], 0 offen lds
	v_add_u32_e32 v12, s50, v14
	s_mov_b32 m0, s1
	v_readfirstlane_b32 s1, v10
	buffer_load_dwordx4 v12, s[44:47], 0 offen lds
	s_mov_b32 m0, s1
	s_lshl_b32 s0, s13, 20
	buffer_load_dwordx4 v4, s[44:47], 0 offen lds
	s_and_b32 s0, s0, 0x400000
	s_add_i32 s1, s8, s0
	s_add_i32 s1, s1, s6
	v_bfe_u32 v1, v2, 4, 2
	v_and_b32_e32 v205, 15, v2
	v_lshrrev_b32_e32 v5, 1, v2
	v_bfe_u32 v6, v2, 1, 3
	v_ashrrev_i32_e32 v212, 8, v2
	v_add_u32_e32 v2, s1, v3
	s_add_i32 s1, s9, s0
	s_add_i32 s1, s1, s6
	v_add3_u32 v216, v2, v9, v7
	v_add_u32_e32 v2, s1, v3
	s_add_i32 s1, s10, s0
	s_add_i32 s1, s1, s6
	s_or_b32 s0, s6, s0
	v_add3_u32 v217, v2, v9, v13
	v_add_u32_e32 v2, s1, v3
	s_add_i32 s0, s0, s11
	v_add3_u32 v218, v2, v9, v11
	v_add_u32_e32 v2, s0, v8
	s_lshl_b32 s0, s36, 20
	s_and_b32 s0, s0, 0xfe000000
	v_readlane_b32 s1, v229, 31
	s_add_i32 s1, s1, s0
	s_lshl_b32 s31, s30, 20
	s_add_i32 s1, s1, s7
	s_add_i32 s1, s1, s31
	v_add3_u32 v219, v2, v3, v9
	v_add_u32_e32 v2, s1, v3
	v_readlane_b32 s1, v229, 32
	s_add_i32 s1, s1, s0
	s_add_i32 s1, s1, s7
	s_add_i32 s1, s1, s31
	v_add3_u32 v220, v2, v9, v7
	v_add_u32_e32 v2, s1, v3
	v_readlane_b32 s1, v229, 33
	s_add_i32 s0, s1, s0
	s_add_i32 s0, s0, s7
	s_add_i32 s0, s0, s31
	v_add3_u32 v221, v2, v9, v13
	v_add_u32_e32 v2, s0, v3
	s_or_b32 s0, s37, s35
	s_or_b32 s0, s0, s30
	s_lshl_b32 s0, s0, 20
	v_readlane_b32 s1, v229, 34
	s_add_i32 s0, s0, s1
	v_add3_u32 v222, v2, v9, v11
	v_add_u32_e32 v2, s0, v8
	v_bitop3_b32 v5, v1, v5, 7 bitop3:0x78
	v_bitop3_b32 v6, v1, v6, 4 bitop3:0x36
	v_add3_u32 v223, v2, v3, v9
	v_mov_b32_e32 v2, 0
	s_ashr_i32 s5, s4, 31
	v_lshlrev_b32_e32 v206, 7, v205
	v_lshlrev_b32_e32 v207, 13, v204
	s_mov_b32 s29, 0
	v_lshlrev_b32_e32 v213, 14, v212
	v_lshlrev_b32_e32 v214, 4, v5
	v_lshlrev_b32_e32 v215, 4, v6
	s_mov_b32 s30, 0
	v_mov_b32_e32 v3, v2
	v_mov_b32_e32 v4, v2
	v_mov_b32_e32 v5, v2
	v_mov_b32_e32 v14, v2
	v_mov_b32_e32 v15, v2
	v_mov_b32_e32 v16, v2
	v_mov_b32_e32 v17, v2
	v_mov_b32_e32 v22, v2
	v_mov_b32_e32 v23, v2
	v_mov_b32_e32 v24, v2
	v_mov_b32_e32 v25, v2
	v_mov_b32_e32 v26, v2
	v_mov_b32_e32 v27, v2
	v_mov_b32_e32 v28, v2
	v_mov_b32_e32 v29, v2
	v_mov_b32_e32 v46, v2
	v_mov_b32_e32 v47, v2
	v_mov_b32_e32 v48, v2
	v_mov_b32_e32 v49, v2
	v_mov_b32_e32 v50, v2
	v_mov_b32_e32 v51, v2
	v_mov_b32_e32 v52, v2
	v_mov_b32_e32 v53, v2
	v_mov_b32_e32 v54, v2
	v_mov_b32_e32 v55, v2
	v_mov_b32_e32 v56, v2
	v_mov_b32_e32 v57, v2
	v_mov_b32_e32 v58, v2
	v_mov_b32_e32 v59, v2
	v_mov_b32_e32 v60, v2
	v_mov_b32_e32 v61, v2
	v_mov_b32_e32 v66, v2
	v_mov_b32_e32 v67, v2
	v_mov_b32_e32 v68, v2
	v_mov_b32_e32 v69, v2
	v_mov_b32_e32 v70, v2
	v_mov_b32_e32 v71, v2
	v_mov_b32_e32 v72, v2
	v_mov_b32_e32 v73, v2
	v_mov_b32_e32 v74, v2
	v_mov_b32_e32 v75, v2
	v_mov_b32_e32 v76, v2
	v_mov_b32_e32 v77, v2
	v_mov_b32_e32 v78, v2
	v_mov_b32_e32 v79, v2
	v_mov_b32_e32 v80, v2
	v_mov_b32_e32 v81, v2
	v_mov_b32_e32 v82, v2
	v_mov_b32_e32 v83, v2
	v_mov_b32_e32 v84, v2
	v_mov_b32_e32 v85, v2
	v_mov_b32_e32 v86, v2
	v_mov_b32_e32 v87, v2
	v_mov_b32_e32 v88, v2
	v_mov_b32_e32 v89, v2
	v_mov_b32_e32 v90, v2
	v_mov_b32_e32 v91, v2
	v_mov_b32_e32 v92, v2
	v_mov_b32_e32 v93, v2
	v_mov_b32_e32 v94, v2
	v_mov_b32_e32 v95, v2
	v_mov_b32_e32 v96, v2
	v_mov_b32_e32 v97, v2
	v_mov_b32_e32 v98, v2
	v_mov_b32_e32 v99, v2
	v_mov_b32_e32 v100, v2
	v_mov_b32_e32 v101, v2
	v_mov_b32_e32 v102, v2
	v_mov_b32_e32 v103, v2
	v_mov_b32_e32 v104, v2
	v_mov_b32_e32 v105, v2
	v_mov_b32_e32 v106, v2
	v_mov_b32_e32 v107, v2
	v_mov_b32_e32 v108, v2
	v_mov_b32_e32 v109, v2
	v_mov_b32_e32 v110, v2
	v_mov_b32_e32 v111, v2
	v_mov_b32_e32 v112, v2
	v_mov_b32_e32 v113, v2
	v_mov_b32_e32 v114, v2
	v_mov_b32_e32 v115, v2
	v_mov_b32_e32 v116, v2
	v_mov_b32_e32 v117, v2
	v_mov_b32_e32 v118, v2
	v_mov_b32_e32 v119, v2
	v_mov_b32_e32 v120, v2
	v_mov_b32_e32 v121, v2
	v_mov_b32_e32 v122, v2
	v_mov_b32_e32 v123, v2
	v_mov_b32_e32 v124, v2
	v_mov_b32_e32 v125, v2
	v_mov_b32_e32 v126, v2
	v_mov_b32_e32 v127, v2
	v_mov_b32_e32 v128, v2
	v_mov_b32_e32 v129, v2
	v_mov_b32_e32 v42, v2
	v_mov_b32_e32 v43, v2
	v_mov_b32_e32 v44, v2
	v_mov_b32_e32 v45, v2
	v_mov_b32_e32 v38, v2
	v_mov_b32_e32 v39, v2
	v_mov_b32_e32 v40, v2
	v_mov_b32_e32 v41, v2
	v_mov_b32_e32 v34, v2
	v_mov_b32_e32 v35, v2
	v_mov_b32_e32 v36, v2
	v_mov_b32_e32 v37, v2
	v_mov_b32_e32 v30, v2
	v_mov_b32_e32 v31, v2
	v_mov_b32_e32 v32, v2
	v_mov_b32_e32 v33, v2
	v_mov_b32_e32 v18, v2
	v_mov_b32_e32 v19, v2
	v_mov_b32_e32 v20, v2
	v_mov_b32_e32 v21, v2
	v_mov_b32_e32 v10, v2
	v_mov_b32_e32 v11, v2
	v_mov_b32_e32 v12, v2
	v_mov_b32_e32 v13, v2
	v_mov_b32_e32 v6, v2
	v_mov_b32_e32 v7, v2
	v_mov_b32_e32 v8, v2
	v_mov_b32_e32 v9, v2
	v_mov_b32_e32 v62, v2
	v_mov_b32_e32 v63, v2
	v_mov_b32_e32 v64, v2
	v_mov_b32_e32 v65, v2
	v_readlane_b32 s63, v230, 21
	v_readlane_b32 s64, v230, 22
	v_readlane_b32 s65, v230, 23
	v_readlane_b32 s66, v230, 24
	v_readlane_b32 s67, v230, 25
	v_readlane_b32 s71, v230, 29
	v_readlane_b32 s72, v230, 30
	v_readlane_b32 s73, v230, 31
	v_readlane_b32 s74, v230, 32
	v_readlane_b32 s75, v230, 33
	v_readfirstlane_b32 s52, v208
	v_add3_u32 v250, v213, v206, v214
	v_add3_u32 v251, v213, v206, v215
	v_add3_u32 v252, v207, v206, v214
	v_add3_u32 v253, v207, v206, v215
	s_mov_b32 s48, 0
	s_mov_b32 s49, 0
	s_waitcnt vmcnt(0)
	s_barrier
	s_add_i32 s76, s52, 0x10000
	s_mov_b32 m0, s76
	s_nop 0
	buffer_load_dwordx4 v223, s[44:47], s49 offen lds
	s_add_u32 m0, s76, 0x400
	s_nop 0
	buffer_load_dwordx4 v222, s[44:47], s49 offen lds
	s_add_u32 m0, s76, 0x800
	s_nop 0
	buffer_load_dwordx4 v221, s[44:47], s49 offen lds
	s_add_u32 m0, s76, 0xc00
	s_nop 0
	buffer_load_dwordx4 v220, s[44:47], s49 offen lds
	s_add_u32 m0, s76, 0x8000
	s_nop 0
	buffer_load_dwordx4 v219, s[44:47], s49 offen lds
	s_add_u32 m0, s76, 0x8400
	s_nop 0
	buffer_load_dwordx4 v218, s[44:47], s49 offen lds
	s_add_u32 m0, s76, 0x8800
	s_nop 0
	buffer_load_dwordx4 v217, s[44:47], s49 offen lds
	s_add_u32 m0, s76, 0x8c00
	s_nop 0
	buffer_load_dwordx4 v216, s[44:47], s49 offen lds
	s_movk_i32 s49, 0x80
	ds_read_b128 v[162:165], v252 offset:32768
	ds_read_b128 v[166:169], v252 offset:34816
	ds_read_b128 v[170:173], v252 offset:36864
	ds_read_b128 v[174:177], v252 offset:38912
	ds_read_b128 v[146:149], v250 offset:8192
	ds_read_b128 v[150:153], v250 offset:10240
	ds_read_b128 v[154:157], v250 offset:12288
	ds_read_b128 v[158:161], v250 offset:14336
	ds_read_b128 v[130:133], v250
	ds_read_b128 v[134:137], v250 offset:2048
	ds_read_b128 v[138:141], v250 offset:4096
	ds_read_b128 v[142:145], v250 offset:6144
	s_movk_i32 s77, 30
.Lp6_steady:
	s_waitcnt lgkmcnt(4)
	v_add_u32_e32 v248, s48, v251
	v_add_u32_e32 v249, s48, v253
	ds_read_b128 v[178:181], v249 offset:32768
	ds_read_b128 v[182:185], v249 offset:34816
	ds_read_b128 v[186:189], v249 offset:36864
	ds_read_b128 v[190:193], v249 offset:38912
	ds_read_b128 v[232:235], v248
	ds_read_b128 v[236:239], v248 offset:2048
	ds_read_b128 v[240:243], v248 offset:4096
	ds_read_b128 v[244:247], v248 offset:6144
	s_waitcnt lgkmcnt(8)
	v_mfma_f32_16x16x32_bf16 v[126:129], v[162:165], v[130:133], v[126:129]
	v_mfma_f32_16x16x32_bf16 v[122:125], v[166:169], v[130:133], v[122:125]
	v_mfma_f32_16x16x32_bf16 v[118:121], v[170:173], v[130:133], v[118:121]
	v_mfma_f32_16x16x32_bf16 v[114:117], v[174:177], v[130:133], v[114:117]
	v_mfma_f32_16x16x32_bf16 v[110:113], v[162:165], v[134:137], v[110:113]
	v_mfma_f32_16x16x32_bf16 v[106:109], v[166:169], v[134:137], v[106:109]
	v_mfma_f32_16x16x32_bf16 v[102:105], v[170:173], v[134:137], v[102:105]
	v_mfma_f32_16x16x32_bf16 v[98:101], v[174:177], v[134:137], v[98:101]
	v_mfma_f32_16x16x32_bf16 v[94:97], v[162:165], v[138:141], v[94:97]
	v_mfma_f32_16x16x32_bf16 v[90:93], v[166:169], v[138:141], v[90:93]
	v_mfma_f32_16x16x32_bf16 v[86:89], v[170:173], v[138:141], v[86:89]
	v_mfma_f32_16x16x32_bf16 v[82:85], v[174:177], v[138:141], v[82:85]
	v_mfma_f32_16x16x32_bf16 v[78:81], v[162:165], v[142:145], v[78:81]
	v_mfma_f32_16x16x32_bf16 v[74:77], v[166:169], v[142:145], v[74:77]
	v_mfma_f32_16x16x32_bf16 v[70:73], v[170:173], v[142:145], v[70:73]
	v_mfma_f32_16x16x32_bf16 v[66:69], v[174:177], v[142:145], v[66:69]
	ds_read_b128 v[130:133], v248 offset:8192
	ds_read_b128 v[134:137], v248 offset:10240
	ds_read_b128 v[138:141], v248 offset:12288
	ds_read_b128 v[142:145], v248 offset:14336
	v_mfma_f32_16x16x32_bf16 v[58:61], v[162:165], v[146:149], v[58:61]
	v_mfma_f32_16x16x32_bf16 v[54:57], v[166:169], v[146:149], v[54:57]
	v_mfma_f32_16x16x32_bf16 v[50:53], v[170:173], v[146:149], v[50:53]
	v_mfma_f32_16x16x32_bf16 v[46:49], v[174:177], v[146:149], v[46:49]
	v_mfma_f32_16x16x32_bf16 v[26:29], v[162:165], v[150:153], v[26:29]
	v_mfma_f32_16x16x32_bf16 v[22:25], v[166:169], v[150:153], v[22:25]
	v_mfma_f32_16x16x32_bf16 v[14:17], v[170:173], v[150:153], v[14:17]
	v_mfma_f32_16x16x32_bf16 v[2:5], v[174:177], v[150:153], v[2:5]
	v_mfma_f32_16x16x32_bf16 v[42:45], v[162:165], v[154:157], v[42:45]
	v_mfma_f32_16x16x32_bf16 v[38:41], v[166:169], v[154:157], v[38:41]
	v_mfma_f32_16x16x32_bf16 v[34:37], v[170:173], v[154:157], v[34:37]
	v_mfma_f32_16x16x32_bf16 v[30:33], v[174:177], v[154:157], v[30:33]
	v_mfma_f32_16x16x32_bf16 v[18:21], v[162:165], v[158:161], v[18:21]
	v_mfma_f32_16x16x32_bf16 v[10:13], v[166:169], v[158:161], v[10:13]
	v_mfma_f32_16x16x32_bf16 v[6:9], v[170:173], v[158:161], v[6:9]
	v_mfma_f32_16x16x32_bf16 v[62:65], v[174:177], v[158:161], v[62:65]
	s_waitcnt lgkmcnt(0)
	s_waitcnt vmcnt(0)
	s_barrier
	s_xor_b32 s53, s48, 0x10000
	s_add_i32 s76, s48, s52
	v_add_u32_e32 v248, s53, v250
	v_add_u32_e32 v249, s53, v252
	ds_read_b128 v[162:165], v249 offset:32768
	ds_read_b128 v[166:169], v249 offset:34816
	ds_read_b128 v[170:173], v249 offset:36864
	ds_read_b128 v[174:177], v249 offset:38912
	ds_read_b128 v[146:149], v248 offset:8192
	ds_read_b128 v[150:153], v248 offset:10240
	ds_read_b128 v[154:157], v248 offset:12288
	ds_read_b128 v[158:161], v248 offset:14336
	v_mfma_f32_16x16x32_bf16 v[58:61], v[178:181], v[130:133], v[58:61]
	s_mov_b32 m0, s76
	v_mfma_f32_16x16x32_bf16 v[54:57], v[182:185], v[130:133], v[54:57]
	buffer_load_dwordx4 v223, s[44:47], s49 offen lds
	v_mfma_f32_16x16x32_bf16 v[50:53], v[186:189], v[130:133], v[50:53]
	v_mfma_f32_16x16x32_bf16 v[46:49], v[190:193], v[130:133], v[46:49]
	v_mfma_f32_16x16x32_bf16 v[26:29], v[178:181], v[134:137], v[26:29]
	s_add_u32 m0, s76, 0x400
	v_mfma_f32_16x16x32_bf16 v[22:25], v[182:185], v[134:137], v[22:25]
	buffer_load_dwordx4 v222, s[44:47], s49 offen lds
	v_mfma_f32_16x16x32_bf16 v[14:17], v[186:189], v[134:137], v[14:17]
	v_mfma_f32_16x16x32_bf16 v[2:5], v[190:193], v[134:137], v[2:5]
	v_mfma_f32_16x16x32_bf16 v[42:45], v[178:181], v[138:141], v[42:45]
	s_add_u32 m0, s76, 0x800
	v_mfma_f32_16x16x32_bf16 v[38:41], v[182:185], v[138:141], v[38:41]
	buffer_load_dwordx4 v221, s[44:47], s49 offen lds
	v_mfma_f32_16x16x32_bf16 v[34:37], v[186:189], v[138:141], v[34:37]
	v_mfma_f32_16x16x32_bf16 v[30:33], v[190:193], v[138:141], v[30:33]
	v_mfma_f32_16x16x32_bf16 v[18:21], v[178:181], v[142:145], v[18:21]
	s_add_u32 m0, s76, 0xc00
	v_mfma_f32_16x16x32_bf16 v[10:13], v[182:185], v[142:145], v[10:13]
	buffer_load_dwordx4 v220, s[44:47], s49 offen lds
	v_mfma_f32_16x16x32_bf16 v[6:9], v[186:189], v[142:145], v[6:9]
	v_mfma_f32_16x16x32_bf16 v[62:65], v[190:193], v[142:145], v[62:65]
	ds_read_b128 v[130:133], v248
	ds_read_b128 v[134:137], v248 offset:2048
	ds_read_b128 v[138:141], v248 offset:4096
	ds_read_b128 v[142:145], v248 offset:6144
	v_mfma_f32_16x16x32_bf16 v[126:129], v[178:181], v[232:235], v[126:129]
	s_add_u32 m0, s76, 0x8000
	v_mfma_f32_16x16x32_bf16 v[122:125], v[182:185], v[232:235], v[122:125]
	buffer_load_dwordx4 v219, s[44:47], s49 offen lds
	v_mfma_f32_16x16x32_bf16 v[118:121], v[186:189], v[232:235], v[118:121]
	v_mfma_f32_16x16x32_bf16 v[114:117], v[190:193], v[232:235], v[114:117]
	v_mfma_f32_16x16x32_bf16 v[110:113], v[178:181], v[236:239], v[110:113]
	s_add_u32 m0, s76, 0x8400
	v_mfma_f32_16x16x32_bf16 v[106:109], v[182:185], v[236:239], v[106:109]
	buffer_load_dwordx4 v218, s[44:47], s49 offen lds
	v_mfma_f32_16x16x32_bf16 v[102:105], v[186:189], v[236:239], v[102:105]
	v_mfma_f32_16x16x32_bf16 v[98:101], v[190:193], v[236:239], v[98:101]
	v_mfma_f32_16x16x32_bf16 v[94:97], v[178:181], v[240:243], v[94:97]
	s_add_u32 m0, s76, 0x8800
	v_mfma_f32_16x16x32_bf16 v[90:93], v[182:185], v[240:243], v[90:93]
	buffer_load_dwordx4 v217, s[44:47], s49 offen lds
	v_mfma_f32_16x16x32_bf16 v[86:89], v[186:189], v[240:243], v[86:89]
	v_mfma_f32_16x16x32_bf16 v[82:85], v[190:193], v[240:243], v[82:85]
	v_mfma_f32_16x16x32_bf16 v[78:81], v[178:181], v[244:247], v[78:81]
	s_add_u32 m0, s76, 0x8c00
	v_mfma_f32_16x16x32_bf16 v[74:77], v[182:185], v[244:247], v[74:77]
	buffer_load_dwordx4 v216, s[44:47], s49 offen lds
	v_mfma_f32_16x16x32_bf16 v[70:73], v[186:189], v[244:247], v[70:73]
	v_mfma_f32_16x16x32_bf16 v[66:69], v[190:193], v[244:247], v[66:69]
	s_xor_b32 s48, s48, 0x10000
	s_addk_i32 s49, 0x80
	s_add_i32 s77, s77, -1
	s_cmp_lg_u32 s77, 0
	s_cbranch_scc1 .Lp6_steady
	s_waitcnt lgkmcnt(4)
	v_add_u32_e32 v248, s48, v251
	v_add_u32_e32 v249, s48, v253
	ds_read_b128 v[178:181], v249 offset:32768
	ds_read_b128 v[182:185], v249 offset:34816
	ds_read_b128 v[186:189], v249 offset:36864
	ds_read_b128 v[190:193], v249 offset:38912
	ds_read_b128 v[232:235], v248
	ds_read_b128 v[236:239], v248 offset:2048
	ds_read_b128 v[240:243], v248 offset:4096
	ds_read_b128 v[244:247], v248 offset:6144
	s_waitcnt lgkmcnt(8)
	v_mfma_f32_16x16x32_bf16 v[126:129], v[162:165], v[130:133], v[126:129]
	v_mfma_f32_16x16x32_bf16 v[122:125], v[166:169], v[130:133], v[122:125]
	v_mfma_f32_16x16x32_bf16 v[118:121], v[170:173], v[130:133], v[118:121]
	v_mfma_f32_16x16x32_bf16 v[114:117], v[174:177], v[130:133], v[114:117]
	v_mfma_f32_16x16x32_bf16 v[110:113], v[162:165], v[134:137], v[110:113]
	v_mfma_f32_16x16x32_bf16 v[106:109], v[166:169], v[134:137], v[106:109]
	v_mfma_f32_16x16x32_bf16 v[102:105], v[170:173], v[134:137], v[102:105]
	v_mfma_f32_16x16x32_bf16 v[98:101], v[174:177], v[134:137], v[98:101]
	v_mfma_f32_16x16x32_bf16 v[94:97], v[162:165], v[138:141], v[94:97]
	v_mfma_f32_16x16x32_bf16 v[90:93], v[166:169], v[138:141], v[90:93]
	v_mfma_f32_16x16x32_bf16 v[86:89], v[170:173], v[138:141], v[86:89]
	v_mfma_f32_16x16x32_bf16 v[82:85], v[174:177], v[138:141], v[82:85]
	v_mfma_f32_16x16x32_bf16 v[78:81], v[162:165], v[142:145], v[78:81]
	v_mfma_f32_16x16x32_bf16 v[74:77], v[166:169], v[142:145], v[74:77]
	v_mfma_f32_16x16x32_bf16 v[70:73], v[170:173], v[142:145], v[70:73]
	v_mfma_f32_16x16x32_bf16 v[66:69], v[174:177], v[142:145], v[66:69]
	ds_read_b128 v[130:133], v248 offset:8192
	ds_read_b128 v[134:137], v248 offset:10240
	ds_read_b128 v[138:141], v248 offset:12288
	ds_read_b128 v[142:145], v248 offset:14336
	v_mfma_f32_16x16x32_bf16 v[58:61], v[162:165], v[146:149], v[58:61]
	v_mfma_f32_16x16x32_bf16 v[54:57], v[166:169], v[146:149], v[54:57]
	v_mfma_f32_16x16x32_bf16 v[50:53], v[170:173], v[146:149], v[50:53]
	v_mfma_f32_16x16x32_bf16 v[46:49], v[174:177], v[146:149], v[46:49]
	v_mfma_f32_16x16x32_bf16 v[26:29], v[162:165], v[150:153], v[26:29]
	v_mfma_f32_16x16x32_bf16 v[22:25], v[166:169], v[150:153], v[22:25]
	v_mfma_f32_16x16x32_bf16 v[14:17], v[170:173], v[150:153], v[14:17]
	v_mfma_f32_16x16x32_bf16 v[2:5], v[174:177], v[150:153], v[2:5]
	v_mfma_f32_16x16x32_bf16 v[42:45], v[162:165], v[154:157], v[42:45]
	v_mfma_f32_16x16x32_bf16 v[38:41], v[166:169], v[154:157], v[38:41]
	v_mfma_f32_16x16x32_bf16 v[34:37], v[170:173], v[154:157], v[34:37]
	v_mfma_f32_16x16x32_bf16 v[30:33], v[174:177], v[154:157], v[30:33]
	v_mfma_f32_16x16x32_bf16 v[18:21], v[162:165], v[158:161], v[18:21]
	v_mfma_f32_16x16x32_bf16 v[10:13], v[166:169], v[158:161], v[10:13]
	v_mfma_f32_16x16x32_bf16 v[6:9], v[170:173], v[158:161], v[6:9]
	v_mfma_f32_16x16x32_bf16 v[62:65], v[174:177], v[158:161], v[62:65]
	s_waitcnt lgkmcnt(0)
	s_waitcnt vmcnt(0)
	s_barrier
	s_xor_b32 s53, s48, 0x10000
	v_add_u32_e32 v248, s53, v250
	v_add_u32_e32 v249, s53, v252
	ds_read_b128 v[162:165], v249 offset:32768
	ds_read_b128 v[166:169], v249 offset:34816
	ds_read_b128 v[170:173], v249 offset:36864
	ds_read_b128 v[174:177], v249 offset:38912
	ds_read_b128 v[146:149], v248 offset:8192
	ds_read_b128 v[150:153], v248 offset:10240
	ds_read_b128 v[154:157], v248 offset:12288
	ds_read_b128 v[158:161], v248 offset:14336
	v_mfma_f32_16x16x32_bf16 v[58:61], v[178:181], v[130:133], v[58:61]
	v_mfma_f32_16x16x32_bf16 v[54:57], v[182:185], v[130:133], v[54:57]
	v_mfma_f32_16x16x32_bf16 v[50:53], v[186:189], v[130:133], v[50:53]
	v_mfma_f32_16x16x32_bf16 v[46:49], v[190:193], v[130:133], v[46:49]
	v_mfma_f32_16x16x32_bf16 v[26:29], v[178:181], v[134:137], v[26:29]
	v_mfma_f32_16x16x32_bf16 v[22:25], v[182:185], v[134:137], v[22:25]
	v_mfma_f32_16x16x32_bf16 v[14:17], v[186:189], v[134:137], v[14:17]
	v_mfma_f32_16x16x32_bf16 v[2:5], v[190:193], v[134:137], v[2:5]
	v_mfma_f32_16x16x32_bf16 v[42:45], v[178:181], v[138:141], v[42:45]
	v_mfma_f32_16x16x32_bf16 v[38:41], v[182:185], v[138:141], v[38:41]
	v_mfma_f32_16x16x32_bf16 v[34:37], v[186:189], v[138:141], v[34:37]
	v_mfma_f32_16x16x32_bf16 v[30:33], v[190:193], v[138:141], v[30:33]
	v_mfma_f32_16x16x32_bf16 v[18:21], v[178:181], v[142:145], v[18:21]
	v_mfma_f32_16x16x32_bf16 v[10:13], v[182:185], v[142:145], v[10:13]
	v_mfma_f32_16x16x32_bf16 v[6:9], v[186:189], v[142:145], v[6:9]
	v_mfma_f32_16x16x32_bf16 v[62:65], v[190:193], v[142:145], v[62:65]
	ds_read_b128 v[130:133], v248
	ds_read_b128 v[134:137], v248 offset:2048
	ds_read_b128 v[138:141], v248 offset:4096
	ds_read_b128 v[142:145], v248 offset:6144
	v_mfma_f32_16x16x32_bf16 v[126:129], v[178:181], v[232:235], v[126:129]
	v_mfma_f32_16x16x32_bf16 v[122:125], v[182:185], v[232:235], v[122:125]
	v_mfma_f32_16x16x32_bf16 v[118:121], v[186:189], v[232:235], v[118:121]
	v_mfma_f32_16x16x32_bf16 v[114:117], v[190:193], v[232:235], v[114:117]
	v_mfma_f32_16x16x32_bf16 v[110:113], v[178:181], v[236:239], v[110:113]
	v_mfma_f32_16x16x32_bf16 v[106:109], v[182:185], v[236:239], v[106:109]
	v_mfma_f32_16x16x32_bf16 v[102:105], v[186:189], v[236:239], v[102:105]
	v_mfma_f32_16x16x32_bf16 v[98:101], v[190:193], v[236:239], v[98:101]
	v_mfma_f32_16x16x32_bf16 v[94:97], v[178:181], v[240:243], v[94:97]
	v_mfma_f32_16x16x32_bf16 v[90:93], v[182:185], v[240:243], v[90:93]
	v_mfma_f32_16x16x32_bf16 v[86:89], v[186:189], v[240:243], v[86:89]
	v_mfma_f32_16x16x32_bf16 v[82:85], v[190:193], v[240:243], v[82:85]
	v_mfma_f32_16x16x32_bf16 v[78:81], v[178:181], v[244:247], v[78:81]
	v_mfma_f32_16x16x32_bf16 v[74:77], v[182:185], v[244:247], v[74:77]
	v_mfma_f32_16x16x32_bf16 v[70:73], v[186:189], v[244:247], v[70:73]
	v_mfma_f32_16x16x32_bf16 v[66:69], v[190:193], v[244:247], v[66:69]
	s_xor_b32 s48, s48, 0x10000
	s_waitcnt lgkmcnt(4)
	v_add_u32_e32 v248, s48, v251
	v_add_u32_e32 v249, s48, v253
	ds_read_b128 v[178:181], v249 offset:32768
	ds_read_b128 v[182:185], v249 offset:34816
	ds_read_b128 v[186:189], v249 offset:36864
	ds_read_b128 v[190:193], v249 offset:38912
	ds_read_b128 v[232:235], v248
	ds_read_b128 v[236:239], v248 offset:2048
	ds_read_b128 v[240:243], v248 offset:4096
	ds_read_b128 v[244:247], v248 offset:6144
	s_waitcnt lgkmcnt(8)
	v_mfma_f32_16x16x32_bf16 v[126:129], v[162:165], v[130:133], v[126:129]
	v_mfma_f32_16x16x32_bf16 v[122:125], v[166:169], v[130:133], v[122:125]
	v_mfma_f32_16x16x32_bf16 v[118:121], v[170:173], v[130:133], v[118:121]
	v_mfma_f32_16x16x32_bf16 v[114:117], v[174:177], v[130:133], v[114:117]
	v_mfma_f32_16x16x32_bf16 v[110:113], v[162:165], v[134:137], v[110:113]
	v_mfma_f32_16x16x32_bf16 v[106:109], v[166:169], v[134:137], v[106:109]
	v_mfma_f32_16x16x32_bf16 v[102:105], v[170:173], v[134:137], v[102:105]
	v_mfma_f32_16x16x32_bf16 v[98:101], v[174:177], v[134:137], v[98:101]
	v_mfma_f32_16x16x32_bf16 v[94:97], v[162:165], v[138:141], v[94:97]
	v_mfma_f32_16x16x32_bf16 v[90:93], v[166:169], v[138:141], v[90:93]
	v_mfma_f32_16x16x32_bf16 v[86:89], v[170:173], v[138:141], v[86:89]
	v_mfma_f32_16x16x32_bf16 v[82:85], v[174:177], v[138:141], v[82:85]
	v_mfma_f32_16x16x32_bf16 v[78:81], v[162:165], v[142:145], v[78:81]
	v_mfma_f32_16x16x32_bf16 v[74:77], v[166:169], v[142:145], v[74:77]
	v_mfma_f32_16x16x32_bf16 v[70:73], v[170:173], v[142:145], v[70:73]
	v_mfma_f32_16x16x32_bf16 v[66:69], v[174:177], v[142:145], v[66:69]
	ds_read_b128 v[130:133], v248 offset:8192
	ds_read_b128 v[134:137], v248 offset:10240
	ds_read_b128 v[138:141], v248 offset:12288
	ds_read_b128 v[142:145], v248 offset:14336
	v_mfma_f32_16x16x32_bf16 v[58:61], v[162:165], v[146:149], v[58:61]
	v_mfma_f32_16x16x32_bf16 v[54:57], v[166:169], v[146:149], v[54:57]
	v_mfma_f32_16x16x32_bf16 v[50:53], v[170:173], v[146:149], v[50:53]
	v_mfma_f32_16x16x32_bf16 v[46:49], v[174:177], v[146:149], v[46:49]
	v_mfma_f32_16x16x32_bf16 v[26:29], v[162:165], v[150:153], v[26:29]
	v_mfma_f32_16x16x32_bf16 v[22:25], v[166:169], v[150:153], v[22:25]
	v_mfma_f32_16x16x32_bf16 v[14:17], v[170:173], v[150:153], v[14:17]
	v_mfma_f32_16x16x32_bf16 v[2:5], v[174:177], v[150:153], v[2:5]
	v_mfma_f32_16x16x32_bf16 v[42:45], v[162:165], v[154:157], v[42:45]
	v_mfma_f32_16x16x32_bf16 v[38:41], v[166:169], v[154:157], v[38:41]
	v_mfma_f32_16x16x32_bf16 v[34:37], v[170:173], v[154:157], v[34:37]
	v_mfma_f32_16x16x32_bf16 v[30:33], v[174:177], v[154:157], v[30:33]
	v_mfma_f32_16x16x32_bf16 v[18:21], v[162:165], v[158:161], v[18:21]
	v_mfma_f32_16x16x32_bf16 v[10:13], v[166:169], v[158:161], v[10:13]
	v_mfma_f32_16x16x32_bf16 v[6:9], v[170:173], v[158:161], v[6:9]
	v_mfma_f32_16x16x32_bf16 v[62:65], v[174:177], v[158:161], v[62:65]
	s_waitcnt lgkmcnt(0)
	v_mfma_f32_16x16x32_bf16 v[58:61], v[178:181], v[130:133], v[58:61]
	v_mfma_f32_16x16x32_bf16 v[54:57], v[182:185], v[130:133], v[54:57]
	v_mfma_f32_16x16x32_bf16 v[50:53], v[186:189], v[130:133], v[50:53]
	v_mfma_f32_16x16x32_bf16 v[46:49], v[190:193], v[130:133], v[46:49]
	v_mfma_f32_16x16x32_bf16 v[26:29], v[178:181], v[134:137], v[26:29]
	v_mfma_f32_16x16x32_bf16 v[22:25], v[182:185], v[134:137], v[22:25]
	v_mfma_f32_16x16x32_bf16 v[14:17], v[186:189], v[134:137], v[14:17]
	v_mfma_f32_16x16x32_bf16 v[2:5], v[190:193], v[134:137], v[2:5]
	v_mfma_f32_16x16x32_bf16 v[42:45], v[178:181], v[138:141], v[42:45]
	v_mfma_f32_16x16x32_bf16 v[38:41], v[182:185], v[138:141], v[38:41]
	v_mfma_f32_16x16x32_bf16 v[34:37], v[186:189], v[138:141], v[34:37]
	v_mfma_f32_16x16x32_bf16 v[30:33], v[190:193], v[138:141], v[30:33]
	v_mfma_f32_16x16x32_bf16 v[18:21], v[178:181], v[142:145], v[18:21]
	v_mfma_f32_16x16x32_bf16 v[10:13], v[182:185], v[142:145], v[10:13]
	v_mfma_f32_16x16x32_bf16 v[6:9], v[186:189], v[142:145], v[6:9]
	v_mfma_f32_16x16x32_bf16 v[62:65], v[190:193], v[142:145], v[62:65]
	v_mfma_f32_16x16x32_bf16 v[126:129], v[178:181], v[232:235], v[126:129]
	v_mfma_f32_16x16x32_bf16 v[122:125], v[182:185], v[232:235], v[122:125]
	v_mfma_f32_16x16x32_bf16 v[118:121], v[186:189], v[232:235], v[118:121]
	v_mfma_f32_16x16x32_bf16 v[114:117], v[190:193], v[232:235], v[114:117]
	v_mfma_f32_16x16x32_bf16 v[110:113], v[178:181], v[236:239], v[110:113]
	v_mfma_f32_16x16x32_bf16 v[106:109], v[182:185], v[236:239], v[106:109]
	v_mfma_f32_16x16x32_bf16 v[102:105], v[186:189], v[236:239], v[102:105]
	v_mfma_f32_16x16x32_bf16 v[98:101], v[190:193], v[236:239], v[98:101]
	v_mfma_f32_16x16x32_bf16 v[94:97], v[178:181], v[240:243], v[94:97]
	v_mfma_f32_16x16x32_bf16 v[90:93], v[182:185], v[240:243], v[90:93]
	v_mfma_f32_16x16x32_bf16 v[86:89], v[186:189], v[240:243], v[86:89]
	v_mfma_f32_16x16x32_bf16 v[82:85], v[190:193], v[240:243], v[82:85]
	v_mfma_f32_16x16x32_bf16 v[78:81], v[178:181], v[244:247], v[78:81]
	v_mfma_f32_16x16x32_bf16 v[74:77], v[182:185], v[244:247], v[74:77]
	v_mfma_f32_16x16x32_bf16 v[70:73], v[186:189], v[244:247], v[70:73]
	v_mfma_f32_16x16x32_bf16 v[66:69], v[190:193], v[244:247], v[66:69]
	s_branch .LBB0_870
